# phase A: k-loop unrolled x2 with loads two k-steps ahead (second register stage), barrier moved before the last 13 MFMAs with next k-step's first fragments read early; hand-written epilogue for plain/
# speedup vs baseline: 1.1546x; 1.0258x over previous
.Ltpa_7:
	s_cmp_eq_u32 s6, 7
	s_cbranch_scc0 .Ltpa_27
	s_add_i32 s7, s7, -48
	s_branch .Ltpa_done
.Ltpa_27:
	s_cmp_eq_u32 s6, 27
	s_cbranch_scc0 .Ltpa_30
	s_add_i32 s7, s7, 24
	s_branch .Ltpa_done
.Ltpa_30:
	s_cmp_eq_u32 s6, 30
	s_cbranch_scc0 .Ltpa_done
	s_add_i32 s7, s7, -24

.LBB0_342:
	v_mov_b32_e32 v6, v41
	s_mul_i32 s2, s8, 0x88000
	v_readlane_b32 s6, v253, 27
	v_readlane_b32 s12, v253, 22
	s_mul_hi_i32 s3, s8, 0x88000
	v_readlane_b32 s7, v253, 28
	s_add_u32 s2, s6, s2
	v_mbcnt_lo_u32_b32 v18, -1, 0
	v_mbcnt_hi_u32_b32 v18, -1, v18
	s_addc_u32 s3, s7, s3
	s_movk_i32 s13, 0x90
	s_waitcnt lgkmcnt(0)
	s_barrier
	v_or_b32_e32 v19, s12, v18
	v_ashrrev_i32_e32 v7, 3, v19
	v_add_u32_e32 v20, 0xe0, v7
	v_lshlrev_b32_e32 v0, 4, v18
	v_and_b32_e32 v40, 0x70, v0
	v_add_u32_e32 v22, 0, v40
	v_mul_lo_u32 v23, v7, s13
	v_add_u32_e32 v24, 0x3600, v23
	v_add_u32_e32 v14, v22, v24
	v_mov_b64_e32 v[0:1], s[2:3]
	v_mad_i64_i32 v[2:3], s[10:11], v7, s33, v[0:1]
	v_lshl_add_u64 v[2:3], v[2:3], 0, v[40:41]
	v_add_u32_e32 v8, v22, v23
	s_waitcnt vmcnt(14)
	ds_write_b128 v8, v[54:57] offset:4608
	v_add_u32_e32 v9, 32, v7
	v_mad_i64_i32 v[4:5], s[10:11], v9, s33, v[0:1]
	v_lshl_add_u64 v[4:5], v[4:5], 0, v[40:41]
	ds_write_b128 v8, v[58:61]
	global_load_dwordx4 v[58:61], v[2:3], off offset:128
	global_load_dwordx4 v[54:57], v[4:5], off offset:128
	s_waitcnt vmcnt(12)
	ds_write_b128 v14, v[62:65]
	v_add_u32_e32 v10, 64, v7
	v_mad_i64_i32 v[2:3], s[10:11], v10, s33, v[0:1]
	v_lshl_add_u64 v[2:3], v[2:3], 0, v[40:41]
	ds_write_b128 v8, v[66:69] offset:9216
	v_add_u32_e32 v11, 0x60, v7
	v_mad_i64_i32 v[4:5], s[10:11], v11, s33, v[0:1]
	v_lshl_add_u64 v[4:5], v[4:5], 0, v[40:41]
	global_load_dwordx4 v[66:69], v[2:3], off offset:128
	global_load_dwordx4 v[62:65], v[4:5], off offset:128
	s_waitcnt vmcnt(10)
	ds_write_b128 v14, v[74:77] offset:9216
	v_add_u32_e32 v15, 0x80, v7
	v_mad_i64_i32 v[2:3], s[10:11], v15, s33, v[0:1]
	v_lshl_add_u64 v[2:3], v[2:3], 0, v[40:41]
	ds_write_b128 v14, v[70:73] offset:4608
	v_add_u32_e32 v16, 0xa0, v7
	v_mad_i64_i32 v[4:5], s[10:11], v16, s33, v[0:1]
	s_mul_hi_i32 s7, s48, 0x88000
	v_add_u32_e32 v17, 0xc0, v7
	s_mul_i32 s6, s48, 0x88000
	s_add_u32 s6, s42, s6
	v_lshl_add_u64 v[4:5], v[4:5], 0, v[40:41]
	global_load_dwordx4 v[70:73], v[2:3], off offset:128
	global_load_dwordx4 v[74:77], v[4:5], off offset:128
	v_mad_i64_i32 v[2:3], s[10:11], v17, s33, v[0:1]
	s_addc_u32 s7, s43, s7
	v_lshl_add_u64 v[2:3], v[2:3], 0, v[40:41]
	v_mad_i64_i32 v[0:1], s[10:11], v20, s33, v[0:1]
	v_lshl_add_u64 v[0:1], v[0:1], 0, v[40:41]
	s_waitcnt vmcnt(9)
	ds_write_b128 v14, v[84:87] offset:13824
	s_waitcnt vmcnt(8)
	ds_write_b128 v14, v[88:91] offset:18432
	global_load_dwordx4 v[84:87], v[2:3], off offset:128
	global_load_dwordx4 v[88:91], v[0:1], off offset:128
	v_mov_b64_e32 v[0:1], s[6:7]
	v_mad_i64_i32 v[4:5], s[10:11], v9, s33, v[0:1]
	v_lshl_add_u64 v[4:5], v[4:5], 0, v[40:41]
	v_accvgpr_write_b32 a239, v6
	v_mad_i64_i32 v[2:3], s[10:11], v7, s33, v[0:1]
	v_lshl_add_u64 v[2:3], v[2:3], 0, v[40:41]
	s_waitcnt vmcnt(15)
	ds_write_b128 v8, v[92:95] offset:36864
	s_waitcnt vmcnt(14)
	ds_write_b128 v8, v[96:99] offset:41472
	global_load_dwordx4 v[92:95], v[2:3], off offset:128
	global_load_dwordx4 v[96:99], v[4:5], off offset:128
	v_mad_i64_i32 v[2:3], s[10:11], v10, s33, v[0:1]
	v_lshl_add_u64 v[2:3], v[2:3], 0, v[40:41]
	v_accvgpr_write_b32 a238, v6
	s_waitcnt vmcnt(15)
	ds_write_b128 v8, v[100:103] offset:46080
	s_waitcnt vmcnt(14)
	ds_write_b128 v14, v[104:107] offset:36864
	v_mad_i64_i32 v[4:5], s[10:11], v11, s33, v[0:1]
	v_lshl_add_u64 v[4:5], v[4:5], 0, v[40:41]
	global_load_dwordx4 v[100:103], v[2:3], off offset:128
	global_load_dwordx4 v[104:107], v[4:5], off offset:128
	v_mad_i64_i32 v[2:3], s[10:11], v15, s33, v[0:1]
	v_lshl_add_u64 v[2:3], v[2:3], 0, v[40:41]
	v_accvgpr_write_b32 a237, v6
	s_waitcnt vmcnt(15)
	ds_write_b128 v14, v[108:111] offset:41472
	s_waitcnt vmcnt(14)
	ds_write_b128 v14, v[112:115] offset:46080
	v_mad_i64_i32 v[4:5], s[10:11], v16, s33, v[0:1]
	v_lshl_add_u64 v[4:5], v[4:5], 0, v[40:41]
	global_load_dwordx4 v[108:111], v[2:3], off offset:128
	global_load_dwordx4 v[112:115], v[4:5], off offset:128
	v_mad_i64_i32 v[2:3], s[10:11], v17, s33, v[0:1]
	v_lshl_add_u64 v[2:3], v[2:3], 0, v[40:41]
	v_accvgpr_write_b32 a236, v6
	v_mad_i64_i32 v[0:1], s[10:11], v20, s33, v[0:1]
	v_lshl_add_u64 v[0:1], v[0:1], 0, v[40:41]
	s_waitcnt vmcnt(15)
	ds_write_b128 v14, v[116:119] offset:50688
	s_waitcnt vmcnt(14)
	ds_write_b128 v14, v[120:123] offset:55296
	global_load_dwordx4 v[116:119], v[2:3], off offset:128
	global_load_dwordx4 v[120:123], v[0:1], off offset:128
	v_accvgpr_write_b32 a235, v6
	v_accvgpr_write_b32 a234, v6
	v_accvgpr_write_b32 a233, v6
	v_accvgpr_write_b32 a232, v6
	v_accvgpr_write_b32 a231, v6
	v_accvgpr_write_b32 a230, v6
	v_accvgpr_write_b32 a229, v6
	v_accvgpr_write_b32 a228, v6
	v_accvgpr_write_b32 a227, v6
	v_accvgpr_write_b32 a226, v6
	v_accvgpr_write_b32 a225, v6
	v_accvgpr_write_b32 a224, v6
	v_accvgpr_write_b32 a255, v6
	v_accvgpr_write_b32 a254, v6
	v_accvgpr_write_b32 a253, v6
	v_accvgpr_write_b32 a252, v6
	v_accvgpr_write_b32 a251, v6
	v_accvgpr_write_b32 a250, v6
	v_accvgpr_write_b32 a249, v6
	v_accvgpr_write_b32 a248, v6
	v_accvgpr_write_b32 a247, v6
	v_accvgpr_write_b32 a246, v6
	v_accvgpr_write_b32 a245, v6
	v_accvgpr_write_b32 a244, v6
	v_accvgpr_write_b32 a243, v6
	v_accvgpr_write_b32 a242, v6
	v_accvgpr_write_b32 a241, v6
	v_accvgpr_write_b32 a240, v6
	v_accvgpr_write_b32 a111, v6
	v_accvgpr_write_b32 a110, v6
	v_accvgpr_write_b32 a109, v6
	v_accvgpr_write_b32 a108, v6
	v_accvgpr_write_b32 a107, v6
	v_accvgpr_write_b32 a106, v6
	v_accvgpr_write_b32 a105, v6
	v_accvgpr_write_b32 a104, v6
	v_accvgpr_write_b32 a103, v6
	v_accvgpr_write_b32 a102, v6
	v_accvgpr_write_b32 a101, v6
	v_accvgpr_write_b32 a100, v6
	v_accvgpr_write_b32 a99, v6
	v_accvgpr_write_b32 a98, v6
	v_accvgpr_write_b32 a97, v6
	v_accvgpr_write_b32 a96, v6
	v_accvgpr_write_b32 a127, v6
	v_accvgpr_write_b32 a126, v6
	v_accvgpr_write_b32 a125, v6
	v_accvgpr_write_b32 a124, v6
	v_accvgpr_write_b32 a123, v6
	v_accvgpr_write_b32 a122, v6
	v_accvgpr_write_b32 a121, v6
	v_accvgpr_write_b32 a120, v6
	v_accvgpr_write_b32 a119, v6
	v_accvgpr_write_b32 a118, v6
	v_accvgpr_write_b32 a117, v6
	v_accvgpr_write_b32 a116, v6
	v_accvgpr_write_b32 a115, v6
	v_accvgpr_write_b32 a114, v6
	v_accvgpr_write_b32 a113, v6
	v_accvgpr_write_b32 a112, v6
	v_accvgpr_write_b32 a207, v6
	v_accvgpr_write_b32 a206, v6
	v_accvgpr_write_b32 a205, v6
	v_accvgpr_write_b32 a204, v6
	v_accvgpr_write_b32 a203, v6
	v_accvgpr_write_b32 a202, v6
	v_accvgpr_write_b32 a201, v6
	v_accvgpr_write_b32 a200, v6
	v_accvgpr_write_b32 a199, v6
	v_accvgpr_write_b32 a198, v6
	v_accvgpr_write_b32 a197, v6
	v_accvgpr_write_b32 a196, v6
	v_accvgpr_write_b32 a195, v6
	v_accvgpr_write_b32 a194, v6
	v_accvgpr_write_b32 a193, v6
	v_accvgpr_write_b32 a192, v6
	v_accvgpr_write_b32 a223, v6
	v_accvgpr_write_b32 a222, v6
	v_accvgpr_write_b32 a221, v6
	v_accvgpr_write_b32 a220, v6
	v_accvgpr_write_b32 a219, v6
	v_accvgpr_write_b32 a218, v6
	v_accvgpr_write_b32 a217, v6
	v_accvgpr_write_b32 a216, v6
	v_accvgpr_write_b32 a215, v6
	v_accvgpr_write_b32 a214, v6
	v_accvgpr_write_b32 a213, v6
	v_accvgpr_write_b32 a212, v6
	v_accvgpr_write_b32 a211, v6
	v_accvgpr_write_b32 a210, v6
	v_accvgpr_write_b32 a209, v6
	v_accvgpr_write_b32 a208, v6
	v_accvgpr_write_b32 a79, v6
	v_accvgpr_write_b32 a78, v6
	v_accvgpr_write_b32 a77, v6
	v_accvgpr_write_b32 a76, v6
	v_accvgpr_write_b32 a75, v6
	v_accvgpr_write_b32 a74, v6
	v_accvgpr_write_b32 a73, v6
	v_accvgpr_write_b32 a72, v6
	v_accvgpr_write_b32 a71, v6
	v_accvgpr_write_b32 a70, v6
	v_accvgpr_write_b32 a69, v6
	v_accvgpr_write_b32 a68, v6
	v_accvgpr_write_b32 a67, v6
	v_accvgpr_write_b32 a66, v6
	v_accvgpr_write_b32 a65, v6
	v_accvgpr_write_b32 a64, v6
	v_accvgpr_write_b32 a95, v6
	v_accvgpr_write_b32 a94, v6
	v_accvgpr_write_b32 a93, v6
	v_accvgpr_write_b32 a92, v6
	v_accvgpr_write_b32 a91, v6
	v_accvgpr_write_b32 a90, v6
	v_accvgpr_write_b32 a89, v6
	v_accvgpr_write_b32 a88, v6
	v_accvgpr_write_b32 a87, v6
	v_accvgpr_write_b32 a86, v6
	v_accvgpr_write_b32 a85, v6
	v_accvgpr_write_b32 a84, v6
	v_accvgpr_write_b32 a83, v6
	v_accvgpr_write_b32 a82, v6
	v_accvgpr_write_b32 a81, v6
	v_accvgpr_write_b32 a80, v6
	v_accvgpr_write_b32 a175, v6
	v_accvgpr_write_b32 a174, v6
	v_accvgpr_write_b32 a173, v6
	v_accvgpr_write_b32 a172, v6
	v_accvgpr_write_b32 a171, v6
	v_accvgpr_write_b32 a170, v6
	v_accvgpr_write_b32 a169, v6
	v_accvgpr_write_b32 a168, v6
	v_accvgpr_write_b32 a167, v6
	v_accvgpr_write_b32 a166, v6
	v_accvgpr_write_b32 a165, v6
	v_accvgpr_write_b32 a164, v6
	v_accvgpr_write_b32 a163, v6
	v_accvgpr_write_b32 a162, v6
	v_accvgpr_write_b32 a161, v6
	v_accvgpr_write_b32 a160, v6
	v_accvgpr_write_b32 a191, v6
	v_accvgpr_write_b32 a190, v6
	v_accvgpr_write_b32 a189, v6
	v_accvgpr_write_b32 a188, v6
	v_accvgpr_write_b32 a187, v6
	v_accvgpr_write_b32 a186, v6
	v_accvgpr_write_b32 a185, v6
	v_accvgpr_write_b32 a184, v6
	v_accvgpr_write_b32 a183, v6
	v_accvgpr_write_b32 a182, v6
	v_accvgpr_write_b32 a181, v6
	v_accvgpr_write_b32 a180, v6
	v_accvgpr_write_b32 a179, v6
	v_accvgpr_write_b32 a178, v6
	v_accvgpr_write_b32 a177, v6
	v_accvgpr_write_b32 a176, v6
	v_accvgpr_write_b32 a47, v6
	v_accvgpr_write_b32 a46, v6
	v_accvgpr_write_b32 a45, v6
	v_accvgpr_write_b32 a44, v6
	v_accvgpr_write_b32 a43, v6
	v_accvgpr_write_b32 a42, v6
	v_accvgpr_write_b32 a41, v6
	v_accvgpr_write_b32 a40, v6
	v_accvgpr_write_b32 a39, v6
	v_accvgpr_write_b32 a38, v6
	v_accvgpr_write_b32 a37, v6
	v_accvgpr_write_b32 a36, v6
	v_accvgpr_write_b32 a35, v6
	v_accvgpr_write_b32 a34, v6
	v_accvgpr_write_b32 a33, v6
	v_accvgpr_write_b32 a32, v6
	v_accvgpr_write_b32 a63, v6
	v_accvgpr_write_b32 a62, v6
	v_accvgpr_write_b32 a61, v6
	v_accvgpr_write_b32 a60, v6
	v_accvgpr_write_b32 a59, v6
	v_accvgpr_write_b32 a58, v6
	v_accvgpr_write_b32 a57, v6
	v_accvgpr_write_b32 a56, v6
	v_accvgpr_write_b32 a55, v6
	v_accvgpr_write_b32 a54, v6
	v_accvgpr_write_b32 a53, v6
	v_accvgpr_write_b32 a52, v6
	v_accvgpr_write_b32 a51, v6
	v_accvgpr_write_b32 a50, v6
	v_accvgpr_write_b32 a49, v6
	v_accvgpr_write_b32 a48, v6
	v_accvgpr_write_b32 a143, v6
	v_accvgpr_write_b32 a142, v6
	v_accvgpr_write_b32 a141, v6
	v_accvgpr_write_b32 a140, v6
	v_accvgpr_write_b32 a139, v6
	v_accvgpr_write_b32 a138, v6
	v_accvgpr_write_b32 a137, v6
	v_accvgpr_write_b32 a136, v6
	v_accvgpr_write_b32 a135, v6
	v_accvgpr_write_b32 a134, v6
	v_accvgpr_write_b32 a133, v6
	v_accvgpr_write_b32 a132, v6
	v_accvgpr_write_b32 a131, v6
	v_accvgpr_write_b32 a130, v6
	v_accvgpr_write_b32 a129, v6
	v_accvgpr_write_b32 a128, v6
	v_accvgpr_write_b32 a159, v6
	v_accvgpr_write_b32 a158, v6
	v_accvgpr_write_b32 a157, v6
	v_accvgpr_write_b32 a156, v6
	v_accvgpr_write_b32 a155, v6
	v_accvgpr_write_b32 a154, v6
	v_accvgpr_write_b32 a153, v6
	v_accvgpr_write_b32 a152, v6
	v_accvgpr_write_b32 a151, v6
	v_accvgpr_write_b32 a150, v6
	v_accvgpr_write_b32 a149, v6
	v_accvgpr_write_b32 a148, v6
	v_accvgpr_write_b32 a147, v6
	v_accvgpr_write_b32 a146, v6
	v_accvgpr_write_b32 a145, v6
	v_accvgpr_write_b32 a144, v6
	v_accvgpr_write_b32 a31, v6
	v_accvgpr_write_b32 a30, v6
	v_accvgpr_write_b32 a29, v6
	v_accvgpr_write_b32 a28, v6
	v_accvgpr_write_b32 a27, v6
	v_accvgpr_write_b32 a26, v6
	v_accvgpr_write_b32 a25, v6
	v_accvgpr_write_b32 a24, v6
	v_accvgpr_write_b32 a23, v6
	v_accvgpr_write_b32 a22, v6
	v_accvgpr_write_b32 a21, v6
	v_accvgpr_write_b32 a20, v6
	v_accvgpr_write_b32 a19, v6
	v_accvgpr_write_b32 a18, v6
	v_accvgpr_write_b32 a17, v6
	v_accvgpr_write_b32 a16, v6
	v_accvgpr_write_b32 a15, v6
	v_accvgpr_write_b32 a14, v6
	v_accvgpr_write_b32 a13, v6
	v_accvgpr_write_b32 a12, v6
	v_accvgpr_write_b32 a11, v6
	v_accvgpr_write_b32 a10, v6
	v_accvgpr_write_b32 a9, v6
	v_accvgpr_write_b32 a8, v6
	v_accvgpr_write_b32 a7, v6
	v_accvgpr_write_b32 a6, v6
	v_accvgpr_write_b32 a5, v6
	v_accvgpr_write_b32 a4, v6
	v_accvgpr_write_b32 a3, v6
	v_accvgpr_write_b32 a2, v6
	v_accvgpr_write_b32 a1, v6
	v_accvgpr_write_b32 a0, v6
	v_mad_i64_i32 v[0:1], s[10:11], v7, s33, 0
	v_mad_i64_i32 v[2:3], s[10:11], v9, s33, 0
	v_mad_i64_i32 v[4:5], s[10:11], v10, s33, 0
	v_mad_i64_i32 v[6:7], s[10:11], v11, s33, 0
	v_mad_i64_i32 v[8:9], s[10:11], v15, s33, 0
	v_mad_i64_i32 v[10:11], s[10:11], v16, s33, 0
	v_mad_i64_i32 v[14:15], s[10:11], v17, s33, 0
	v_mad_i64_i32 v[16:17], s[10:11], v20, s33, 0
	v_mov_b32_e32 v21, s12
	s_mov_b32 s10, 0xfffff9f
	v_and_b32_e32 v20, 31, v18
	v_bitop3_b32 v21, v18, s10, v21 bitop3:0xc8
	v_lshrrev_b32_e32 v18, 1, v18
	s_movk_i32 s9, 0x80
	s_waitcnt lgkmcnt(0)
	s_barrier
	v_and_b32_e32 v27, 16, v18
	v_lshlrev_b32_e32 v18, 1, v19
	v_and_or_b32 v18, v18, s9, v20
	v_mul_lo_u32 v25, v21, s13
	v_mul_u32_u24_e32 v26, 0x90, v18
	v_lshl_add_u64 v[18:19], s[2:3], 0, v[40:41]
	v_lshl_add_u64 v[20:21], s[6:7], 0, v[40:41]
	v_add_u32_e32 v27, 0, v27
	s_mov_b32 s2, 0
	v_lshl_add_u64 v[250:251], v[18:19], 0, v[0:1]
	global_load_dwordx4 v[186:189], v[250:251], off offset:256
	v_lshl_add_u64 v[250:251], v[18:19], 0, v[2:3]
	global_load_dwordx4 v[190:193], v[250:251], off offset:256
	v_lshl_add_u64 v[250:251], v[20:21], 0, v[0:1]
	global_load_dwordx4 v[194:197], v[250:251], off offset:256
	v_lshl_add_u64 v[250:251], v[20:21], 0, v[2:3]
	global_load_dwordx4 v[198:201], v[250:251], off offset:256
	v_lshl_add_u64 v[250:251], v[18:19], 0, v[4:5]
	global_load_dwordx4 v[202:205], v[250:251], off offset:256
	v_lshl_add_u64 v[250:251], v[18:19], 0, v[6:7]
	global_load_dwordx4 v[206:209], v[250:251], off offset:256
	v_lshl_add_u64 v[250:251], v[20:21], 0, v[4:5]
	global_load_dwordx4 v[210:213], v[250:251], off offset:256
	v_lshl_add_u64 v[250:251], v[20:21], 0, v[6:7]
	global_load_dwordx4 v[214:217], v[250:251], off offset:256
	v_lshl_add_u64 v[250:251], v[18:19], 0, v[8:9]
	global_load_dwordx4 v[218:221], v[250:251], off offset:256
	v_lshl_add_u64 v[250:251], v[18:19], 0, v[10:11]
	global_load_dwordx4 v[222:225], v[250:251], off offset:256
	v_lshl_add_u64 v[250:251], v[20:21], 0, v[8:9]
	global_load_dwordx4 v[226:229], v[250:251], off offset:256
	v_lshl_add_u64 v[250:251], v[20:21], 0, v[10:11]
	global_load_dwordx4 v[230:233], v[250:251], off offset:256
	v_lshl_add_u64 v[250:251], v[18:19], 0, v[14:15]
	global_load_dwordx4 v[234:237], v[250:251], off offset:256
	v_lshl_add_u64 v[250:251], v[18:19], 0, v[16:17]
	global_load_dwordx4 v[238:241], v[250:251], off offset:256
	v_lshl_add_u64 v[250:251], v[20:21], 0, v[14:15]
	global_load_dwordx4 v[242:245], v[250:251], off offset:256
	v_lshl_add_u64 v[250:251], v[20:21], 0, v[16:17]
	global_load_dwordx4 v[246:249], v[250:251], off offset:256
	v_add_u32_e32 v40, v27, v25
	v_add_u32_e32 v49, v27, v26
	ds_read_b128 v[50:53], v40 offset:4608
	ds_read_b128 v[128:131], v49 offset:36864
	ds_read_b128 v[168:171], v49 offset:41472
	ds_read_b128 v[136:139], v49 offset:46080
	ds_read_b128 v[176:179], v49 offset:50688
	ds_read_b128 v[144:147], v40
	ds_read_b128 v[152:155], v40 offset:9216
	ds_read_b128 v[160:163], v40 offset:13824
.LBB0_343:
	s_add_i32 s3, s2, 1
	s_bitcmp1_b32 s3, 0
	s_cselect_b32 s6, 0x12000, 0
	s_add_i32 s7, s9, 64
	s_cmp_lt_u32 s2, 13
	s_cselect_b32 s90, s7, 0
	v_add_u32_e32 v184, s6, v22
	v_add_u32_e32 v185, v184, v23
	s_waitcnt lgkmcnt(6)
	v_mfma_f32_32x32x16_f16 a[192:207], v[50:53], v[128:131], a[192:207]
	ds_read_b128 v[124:127], v40 offset:4640
	ds_read_b128 v[132:135], v49 offset:36896
	ds_read_b128 v[140:143], v49 offset:46112
	s_waitcnt lgkmcnt(8)
	v_mfma_f32_32x32x16_f16 a[208:223], v[50:53], v[168:171], a[208:223]
	ds_read_b128 v[148:151], v40 offset:32
	ds_read_b128 v[156:159], v40 offset:9248
	ds_read_b128 v[164:167], v40 offset:13856
	s_waitcnt lgkmcnt(10)
	v_mfma_f32_32x32x16_f16 a[64:79], v[50:53], v[136:139], a[64:79]
	ds_read_b128 v[172:175], v49 offset:41504
	ds_read_b128 v[180:183], v49 offset:50720
	s_lshl_b64 s[6:7], s[90:91], 1
	s_waitcnt lgkmcnt(11)
	v_mfma_f32_32x32x16_f16 a[80:95], v[50:53], v[176:179], a[80:95]
	v_lshl_add_u64 v[28:29], v[18:19], 0, s[6:7]
	v_lshl_add_u64 v[78:79], v[20:21], 0, s[6:7]
	ds_read_b128 v[50:53], v40 offset:64
	s_waitcnt lgkmcnt(11)
	v_mfma_f32_32x32x16_f16 a[224:239], v[144:147], v[128:131], a[224:239]
	v_add_u32_e32 v184, v184, v24
	s_waitcnt vmcnt(31)
	ds_write_b128 v185, v[58:61]
	v_mfma_f32_32x32x16_f16 a[240:255], v[144:147], v[168:171], a[240:255]
	v_lshl_add_u64 v[250:251], v[28:29], 0, v[0:1]
	global_load_dwordx4 v[58:61], v[250:251], off
	v_mfma_f32_32x32x16_f16 a[96:111], v[144:147], v[136:139], a[96:111]
	s_waitcnt vmcnt(31)
	ds_write_b128 v185, v[54:57] offset:4608
	v_lshl_add_u64 v[250:251], v[28:29], 0, v[2:3]
	v_mfma_f32_32x32x16_f16 a[112:127], v[144:147], v[176:179], a[112:127]
	ds_read_b128 v[144:147], v40 offset:13888
	global_load_dwordx4 v[54:57], v[250:251], off
	s_waitcnt lgkmcnt(13)
	v_mfma_f32_32x32x16_f16 a[160:175], v[152:155], v[128:131], a[160:175]
	s_waitcnt vmcnt(25)
	ds_write_b128 v185, v[92:95] offset:36864
	v_lshl_add_u64 v[250:251], v[78:79], 0, v[0:1]
	v_mfma_f32_32x32x16_f16 a[176:191], v[152:155], v[168:171], a[176:191]
	global_load_dwordx4 v[92:95], v[250:251], off
	v_mfma_f32_32x32x16_f16 a[32:47], v[152:155], v[136:139], a[32:47]
	s_waitcnt vmcnt(25)
	ds_write_b128 v185, v[96:99] offset:41472
	v_lshl_add_u64 v[250:251], v[78:79], 0, v[2:3]
	v_mfma_f32_32x32x16_f16 a[48:63], v[152:155], v[176:179], a[48:63]
	ds_read_b128 v[152:155], v49 offset:36928
	global_load_dwordx4 v[96:99], v[250:251], off
	s_waitcnt lgkmcnt(15)
	v_mfma_f32_32x32x16_f16 a[128:143], v[160:163], v[128:131], a[128:143]
	ds_read_b128 v[128:131], v40 offset:4672
	v_mfma_f32_32x32x16_f16 a[144:159], v[160:163], v[168:171], a[144:159]
	ds_read_b128 v[168:171], v49 offset:46144
	ds_write_b128 v185, v[66:69] offset:9216
	v_mfma_f32_32x32x16_f16 a[16:31], v[160:163], v[136:139], a[16:31]
	ds_read_b128 v[136:139], v40 offset:9280
	v_lshl_add_u64 v[250:251], v[28:29], 0, v[4:5]
	global_load_dwordx4 v[66:69], v[250:251], off
	v_mfma_f32_32x32x16_f16 a[0:15], v[160:163], v[176:179], a[0:15]
	ds_read_b128 v[160:163], v49 offset:41536
	ds_read_b128 v[176:179], v49 offset:50752
	s_waitcnt lgkmcnt(15)
	v_mfma_f32_32x32x16_f16 a[224:239], v[148:151], v[132:135], a[224:239]
	ds_write_b128 v185, v[62:65] offset:13824
	v_lshl_add_u64 v[250:251], v[28:29], 0, v[6:7]
	s_waitcnt lgkmcnt(15)
	v_mfma_f32_32x32x16_f16 a[240:255], v[148:151], v[172:175], a[240:255]
	global_load_dwordx4 v[62:65], v[250:251], off
	v_mfma_f32_32x32x16_f16 a[96:111], v[148:151], v[140:143], a[96:111]
	s_waitcnt vmcnt(27)
	ds_write_b128 v185, v[100:103] offset:46080
	v_lshl_add_u64 v[250:251], v[78:79], 0, v[4:5]
	s_waitcnt lgkmcnt(15)
	v_mfma_f32_32x32x16_f16 a[112:127], v[148:151], v[180:183], a[112:127]
	ds_read_b128 v[148:151], v40 offset:13920
	global_load_dwordx4 v[100:103], v[250:251], off
	v_mfma_f32_32x32x16_f16 a[192:207], v[124:127], v[132:135], a[192:207]
	v_mfma_f32_32x32x16_f16 a[208:223], v[124:127], v[172:175], a[208:223]
	s_waitcnt vmcnt(27)
	ds_write_b128 v185, v[104:107] offset:50688
	v_lshl_add_u64 v[250:251], v[78:79], 0, v[6:7]
	v_mfma_f32_32x32x16_f16 a[64:79], v[124:127], v[140:143], a[64:79]
	global_load_dwordx4 v[104:107], v[250:251], off
	v_mfma_f32_32x32x16_f16 a[80:95], v[124:127], v[180:183], a[80:95]
	ds_read_b128 v[124:127], v40 offset:96
	v_mfma_f32_32x32x16_f16 a[160:175], v[156:159], v[132:135], a[160:175]
	ds_write_b128 v185, v[70:73] offset:18432
	v_lshl_add_u64 v[250:251], v[28:29], 0, v[8:9]
	v_mfma_f32_32x32x16_f16 a[176:191], v[156:159], v[172:175], a[176:191]
	global_load_dwordx4 v[70:73], v[250:251], off
	v_mfma_f32_32x32x16_f16 a[32:47], v[156:159], v[140:143], a[32:47]
	v_mfma_f32_32x32x16_f16 a[48:63], v[156:159], v[180:183], a[48:63]
	ds_read_b128 v[156:159], v49 offset:36960
	ds_write_b128 v185, v[74:77] offset:23040
	v_mfma_f32_32x32x16_f16 a[128:143], v[164:167], v[132:135], a[128:143]
	ds_read_b128 v[132:135], v40 offset:4704
	v_lshl_add_u64 v[250:251], v[28:29], 0, v[10:11]
	global_load_dwordx4 v[74:77], v[250:251], off
	v_mfma_f32_32x32x16_f16 a[144:159], v[164:167], v[172:175], a[144:159]
	ds_read_b128 v[172:175], v49 offset:46176
	v_mfma_f32_32x32x16_f16 a[16:31], v[164:167], v[140:143], a[16:31]
	ds_read_b128 v[140:143], v40 offset:9312
	s_waitcnt vmcnt(29)
	ds_write_b128 v185, v[108:111] offset:55296
	v_mfma_f32_32x32x16_f16 a[0:15], v[164:167], v[180:183], a[0:15]
	ds_read_b128 v[164:167], v49 offset:41568
	ds_read_b128 v[180:183], v49 offset:50784
	v_lshl_add_u64 v[250:251], v[78:79], 0, v[8:9]
	s_waitcnt lgkmcnt(15)
	v_mfma_f32_32x32x16_f16 a[224:239], v[50:53], v[152:155], a[224:239]
	global_load_dwordx4 v[108:111], v[250:251], off
	s_waitcnt vmcnt(29)
	ds_write_b128 v185, v[112:115] offset:59904
	v_mfma_f32_32x32x16_f16 a[240:255], v[50:53], v[160:163], a[240:255]
	v_lshl_add_u64 v[250:251], v[78:79], 0, v[10:11]
	global_load_dwordx4 v[112:115], v[250:251], off
	v_mfma_f32_32x32x16_f16 a[96:111], v[50:53], v[168:171], a[96:111]
	s_waitcnt lgkmcnt(15)
	v_mfma_f32_32x32x16_f16 a[112:127], v[50:53], v[176:179], a[112:127]
	ds_write_b128 v185, v[84:87] offset:27648
	v_lshl_add_u64 v[250:251], v[28:29], 0, v[14:15]
	v_mfma_f32_32x32x16_f16 a[192:207], v[128:131], v[152:155], a[192:207]
	global_load_dwordx4 v[84:87], v[250:251], off
	v_mfma_f32_32x32x16_f16 a[208:223], v[128:131], v[160:163], a[208:223]
	v_mfma_f32_32x32x16_f16 a[64:79], v[128:131], v[168:171], a[64:79]
	s_bitcmp1_b32 s3, 0
	s_cselect_b32 s6, 0x12000, 0
	v_add_u32_e32 v40, s6, v27
	v_add_u32_e32 v49, v40, v26
	v_add_u32_e32 v40, v40, v25
	v_mfma_f32_32x32x16_f16 a[80:95], v[128:131], v[176:179], a[80:95]
	ds_write_b128 v185, v[88:91] offset:32256
	v_lshl_add_u64 v[250:251], v[28:29], 0, v[16:17]
	v_mfma_f32_32x32x16_f16 a[160:175], v[136:139], v[152:155], a[160:175]
	global_load_dwordx4 v[88:91], v[250:251], off
	v_mfma_f32_32x32x16_f16 a[176:191], v[136:139], v[160:163], a[176:191]
	s_waitcnt vmcnt(31)
	ds_write_b128 v185, v[116:119] offset:64512
	v_lshl_add_u64 v[250:251], v[78:79], 0, v[14:15]
	v_mfma_f32_32x32x16_f16 a[32:47], v[136:139], v[168:171], a[32:47]
	global_load_dwordx4 v[116:119], v[250:251], off
	v_mfma_f32_32x32x16_f16 a[48:63], v[136:139], v[176:179], a[48:63]
	v_mfma_f32_32x32x16_f16 a[128:143], v[144:147], v[152:155], a[128:143]
	s_waitcnt vmcnt(31)
	ds_write_b128 v184, v[120:123] offset:55296
	v_lshl_add_u64 v[250:251], v[78:79], 0, v[16:17]
	v_mfma_f32_32x32x16_f16 a[144:159], v[144:147], v[160:163], a[144:159]
	global_load_dwordx4 v[120:123], v[250:251], off
	v_mfma_f32_32x32x16_f16 a[16:31], v[144:147], v[168:171], a[16:31]
	v_mfma_f32_32x32x16_f16 a[0:15], v[144:147], v[176:179], a[0:15]
	s_waitcnt lgkmcnt(12)
	v_mfma_f32_32x32x16_f16 a[224:239], v[124:127], v[156:159], a[224:239]
	s_waitcnt lgkmcnt(6)
	v_mfma_f32_32x32x16_f16 a[240:255], v[124:127], v[164:167], a[240:255]
	v_mfma_f32_32x32x16_f16 a[96:111], v[124:127], v[172:175], a[96:111]
	s_waitcnt lgkmcnt(0)
	s_barrier
	ds_read_b128 v[50:53], v40 offset:4608
	ds_read_b128 v[128:131], v49 offset:36864
	v_mfma_f32_32x32x16_f16 a[112:127], v[124:127], v[180:183], a[112:127]
	ds_read_b128 v[168:171], v49 offset:41472
	ds_read_b128 v[136:139], v49 offset:46080
	ds_read_b128 v[176:179], v49 offset:50688
	v_mfma_f32_32x32x16_f16 a[192:207], v[132:135], v[156:159], a[192:207]
	ds_read_b128 v[144:147], v40
	ds_read_b128 v[152:155], v40 offset:9216
	ds_read_b128 v[160:163], v40 offset:13824
	v_mfma_f32_32x32x16_f16 a[208:223], v[132:135], v[164:167], a[208:223]
	v_mfma_f32_32x32x16_f16 a[64:79], v[132:135], v[172:175], a[64:79]
	v_mfma_f32_32x32x16_f16 a[80:95], v[132:135], v[180:183], a[80:95]
	v_mfma_f32_32x32x16_f16 a[160:175], v[140:143], v[156:159], a[160:175]
	v_mfma_f32_32x32x16_f16 a[176:191], v[140:143], v[164:167], a[176:191]
	v_mfma_f32_32x32x16_f16 a[32:47], v[140:143], v[172:175], a[32:47]
	v_mfma_f32_32x32x16_f16 a[48:63], v[140:143], v[180:183], a[48:63]
	v_mfma_f32_32x32x16_f16 a[128:143], v[148:151], v[156:159], a[128:143]
	v_mfma_f32_32x32x16_f16 a[144:159], v[148:151], v[164:167], a[144:159]
	v_mfma_f32_32x32x16_f16 a[16:31], v[148:151], v[172:175], a[16:31]
	v_mfma_f32_32x32x16_f16 a[0:15], v[148:151], v[180:183], a[0:15]
	s_add_i32 s9, s9, 64
	s_mov_b32 s2, s3
	s_add_i32 s3, s2, 1
	s_bitcmp1_b32 s3, 0
	s_cselect_b32 s6, 0x12000, 0
	s_add_i32 s7, s9, 64
	s_cmp_lt_u32 s2, 13
	s_cselect_b32 s90, s7, 0
	v_add_u32_e32 v184, s6, v22
	v_add_u32_e32 v185, v184, v23
	s_waitcnt lgkmcnt(6)
	v_mfma_f32_32x32x16_f16 a[192:207], v[50:53], v[128:131], a[192:207]
	ds_read_b128 v[124:127], v40 offset:4640
	ds_read_b128 v[132:135], v49 offset:36896
	ds_read_b128 v[140:143], v49 offset:46112
	s_waitcnt lgkmcnt(8)
	v_mfma_f32_32x32x16_f16 a[208:223], v[50:53], v[168:171], a[208:223]
	ds_read_b128 v[148:151], v40 offset:32
	ds_read_b128 v[156:159], v40 offset:9248
	ds_read_b128 v[164:167], v40 offset:13856
	s_waitcnt lgkmcnt(10)
	v_mfma_f32_32x32x16_f16 a[64:79], v[50:53], v[136:139], a[64:79]
	ds_read_b128 v[172:175], v49 offset:41504
	ds_read_b128 v[180:183], v49 offset:50720
	s_lshl_b64 s[6:7], s[90:91], 1
	s_waitcnt lgkmcnt(11)
	v_mfma_f32_32x32x16_f16 a[80:95], v[50:53], v[176:179], a[80:95]
	v_lshl_add_u64 v[28:29], v[18:19], 0, s[6:7]
	v_lshl_add_u64 v[78:79], v[20:21], 0, s[6:7]
	ds_read_b128 v[50:53], v40 offset:64
	s_waitcnt lgkmcnt(11)
	v_mfma_f32_32x32x16_f16 a[224:239], v[144:147], v[128:131], a[224:239]
	v_add_u32_e32 v184, v184, v24
	s_waitcnt vmcnt(31)
	ds_write_b128 v185, v[186:189]
	v_mfma_f32_32x32x16_f16 a[240:255], v[144:147], v[168:171], a[240:255]
	v_lshl_add_u64 v[250:251], v[28:29], 0, v[0:1]
	global_load_dwordx4 v[186:189], v[250:251], off
	v_mfma_f32_32x32x16_f16 a[96:111], v[144:147], v[136:139], a[96:111]
	s_waitcnt vmcnt(31)
	ds_write_b128 v185, v[190:193] offset:4608
	v_lshl_add_u64 v[250:251], v[28:29], 0, v[2:3]
	v_mfma_f32_32x32x16_f16 a[112:127], v[144:147], v[176:179], a[112:127]
	ds_read_b128 v[144:147], v40 offset:13888
	global_load_dwordx4 v[190:193], v[250:251], off
	s_waitcnt lgkmcnt(13)
	v_mfma_f32_32x32x16_f16 a[160:175], v[152:155], v[128:131], a[160:175]
	s_waitcnt vmcnt(31)
	ds_write_b128 v185, v[194:197] offset:36864
	v_lshl_add_u64 v[250:251], v[78:79], 0, v[0:1]
	v_mfma_f32_32x32x16_f16 a[176:191], v[152:155], v[168:171], a[176:191]
	global_load_dwordx4 v[194:197], v[250:251], off
	v_mfma_f32_32x32x16_f16 a[32:47], v[152:155], v[136:139], a[32:47]
	s_waitcnt vmcnt(31)
	ds_write_b128 v185, v[198:201] offset:41472
	v_lshl_add_u64 v[250:251], v[78:79], 0, v[2:3]
	v_mfma_f32_32x32x16_f16 a[48:63], v[152:155], v[176:179], a[48:63]
	ds_read_b128 v[152:155], v49 offset:36928
	global_load_dwordx4 v[198:201], v[250:251], off
	s_waitcnt lgkmcnt(15)
	v_mfma_f32_32x32x16_f16 a[128:143], v[160:163], v[128:131], a[128:143]
	ds_read_b128 v[128:131], v40 offset:4672
	v_mfma_f32_32x32x16_f16 a[144:159], v[160:163], v[168:171], a[144:159]
	ds_read_b128 v[168:171], v49 offset:46144
	s_waitcnt vmcnt(31)
	ds_write_b128 v185, v[202:205] offset:9216
	v_mfma_f32_32x32x16_f16 a[16:31], v[160:163], v[136:139], a[16:31]
	ds_read_b128 v[136:139], v40 offset:9280
	v_lshl_add_u64 v[250:251], v[28:29], 0, v[4:5]
	global_load_dwordx4 v[202:205], v[250:251], off
	v_mfma_f32_32x32x16_f16 a[0:15], v[160:163], v[176:179], a[0:15]
	ds_read_b128 v[160:163], v49 offset:41536
	ds_read_b128 v[176:179], v49 offset:50752
	s_waitcnt lgkmcnt(15)
	v_mfma_f32_32x32x16_f16 a[224:239], v[148:151], v[132:135], a[224:239]
	s_waitcnt vmcnt(31)
	ds_write_b128 v185, v[206:209] offset:13824
	v_lshl_add_u64 v[250:251], v[28:29], 0, v[6:7]
	s_waitcnt lgkmcnt(15)
	v_mfma_f32_32x32x16_f16 a[240:255], v[148:151], v[172:175], a[240:255]
	global_load_dwordx4 v[206:209], v[250:251], off
	v_mfma_f32_32x32x16_f16 a[96:111], v[148:151], v[140:143], a[96:111]
	s_waitcnt vmcnt(31)
	ds_write_b128 v185, v[210:213] offset:46080
	v_lshl_add_u64 v[250:251], v[78:79], 0, v[4:5]
	s_waitcnt lgkmcnt(15)
	v_mfma_f32_32x32x16_f16 a[112:127], v[148:151], v[180:183], a[112:127]
	ds_read_b128 v[148:151], v40 offset:13920
	global_load_dwordx4 v[210:213], v[250:251], off
	v_mfma_f32_32x32x16_f16 a[192:207], v[124:127], v[132:135], a[192:207]
	v_mfma_f32_32x32x16_f16 a[208:223], v[124:127], v[172:175], a[208:223]
	s_waitcnt vmcnt(31)
	ds_write_b128 v185, v[214:217] offset:50688
	v_lshl_add_u64 v[250:251], v[78:79], 0, v[6:7]
	v_mfma_f32_32x32x16_f16 a[64:79], v[124:127], v[140:143], a[64:79]
	global_load_dwordx4 v[214:217], v[250:251], off
	v_mfma_f32_32x32x16_f16 a[80:95], v[124:127], v[180:183], a[80:95]
	ds_read_b128 v[124:127], v40 offset:96
	v_mfma_f32_32x32x16_f16 a[160:175], v[156:159], v[132:135], a[160:175]
	s_waitcnt vmcnt(31)
	ds_write_b128 v185, v[218:221] offset:18432
	v_lshl_add_u64 v[250:251], v[28:29], 0, v[8:9]
	v_mfma_f32_32x32x16_f16 a[176:191], v[156:159], v[172:175], a[176:191]
	global_load_dwordx4 v[218:221], v[250:251], off
	v_mfma_f32_32x32x16_f16 a[32:47], v[156:159], v[140:143], a[32:47]
	v_mfma_f32_32x32x16_f16 a[48:63], v[156:159], v[180:183], a[48:63]
	ds_read_b128 v[156:159], v49 offset:36960
	s_waitcnt vmcnt(31)
	ds_write_b128 v185, v[222:225] offset:23040
	v_mfma_f32_32x32x16_f16 a[128:143], v[164:167], v[132:135], a[128:143]
	ds_read_b128 v[132:135], v40 offset:4704
	v_lshl_add_u64 v[250:251], v[28:29], 0, v[10:11]
	global_load_dwordx4 v[222:225], v[250:251], off
	v_mfma_f32_32x32x16_f16 a[144:159], v[164:167], v[172:175], a[144:159]
	ds_read_b128 v[172:175], v49 offset:46176
	v_mfma_f32_32x32x16_f16 a[16:31], v[164:167], v[140:143], a[16:31]
	ds_read_b128 v[140:143], v40 offset:9312
	s_waitcnt vmcnt(31)
	ds_write_b128 v185, v[226:229] offset:55296
	v_mfma_f32_32x32x16_f16 a[0:15], v[164:167], v[180:183], a[0:15]
	ds_read_b128 v[164:167], v49 offset:41568
	ds_read_b128 v[180:183], v49 offset:50784
	v_lshl_add_u64 v[250:251], v[78:79], 0, v[8:9]
	s_waitcnt lgkmcnt(15)
	v_mfma_f32_32x32x16_f16 a[224:239], v[50:53], v[152:155], a[224:239]
	global_load_dwordx4 v[226:229], v[250:251], off
	s_waitcnt vmcnt(31)
	ds_write_b128 v185, v[230:233] offset:59904
	v_mfma_f32_32x32x16_f16 a[240:255], v[50:53], v[160:163], a[240:255]
	v_lshl_add_u64 v[250:251], v[78:79], 0, v[10:11]
	global_load_dwordx4 v[230:233], v[250:251], off
	v_mfma_f32_32x32x16_f16 a[96:111], v[50:53], v[168:171], a[96:111]
	s_waitcnt lgkmcnt(15)
	v_mfma_f32_32x32x16_f16 a[112:127], v[50:53], v[176:179], a[112:127]
	s_waitcnt vmcnt(31)
	ds_write_b128 v185, v[234:237] offset:27648
	v_lshl_add_u64 v[250:251], v[28:29], 0, v[14:15]
	v_mfma_f32_32x32x16_f16 a[192:207], v[128:131], v[152:155], a[192:207]
	global_load_dwordx4 v[234:237], v[250:251], off
	v_mfma_f32_32x32x16_f16 a[208:223], v[128:131], v[160:163], a[208:223]
	v_mfma_f32_32x32x16_f16 a[64:79], v[128:131], v[168:171], a[64:79]
	s_bitcmp1_b32 s3, 0
	s_cselect_b32 s6, 0x12000, 0
	v_add_u32_e32 v40, s6, v27
	v_add_u32_e32 v49, v40, v26
	v_add_u32_e32 v40, v40, v25
	v_mfma_f32_32x32x16_f16 a[80:95], v[128:131], v[176:179], a[80:95]
	s_waitcnt vmcnt(31)
	ds_write_b128 v185, v[238:241] offset:32256
	v_lshl_add_u64 v[250:251], v[28:29], 0, v[16:17]
	v_mfma_f32_32x32x16_f16 a[160:175], v[136:139], v[152:155], a[160:175]
	global_load_dwordx4 v[238:241], v[250:251], off
	v_mfma_f32_32x32x16_f16 a[176:191], v[136:139], v[160:163], a[176:191]
	s_waitcnt vmcnt(31)
	ds_write_b128 v185, v[242:245] offset:64512
	v_lshl_add_u64 v[250:251], v[78:79], 0, v[14:15]
	v_mfma_f32_32x32x16_f16 a[32:47], v[136:139], v[168:171], a[32:47]
	global_load_dwordx4 v[242:245], v[250:251], off
	v_mfma_f32_32x32x16_f16 a[48:63], v[136:139], v[176:179], a[48:63]
	v_mfma_f32_32x32x16_f16 a[128:143], v[144:147], v[152:155], a[128:143]
	s_waitcnt vmcnt(31)
	ds_write_b128 v184, v[246:249] offset:55296
	v_lshl_add_u64 v[250:251], v[78:79], 0, v[16:17]
	v_mfma_f32_32x32x16_f16 a[144:159], v[144:147], v[160:163], a[144:159]
	global_load_dwordx4 v[246:249], v[250:251], off
	v_mfma_f32_32x32x16_f16 a[16:31], v[144:147], v[168:171], a[16:31]
	v_mfma_f32_32x32x16_f16 a[0:15], v[144:147], v[176:179], a[0:15]
	s_waitcnt lgkmcnt(12)
	v_mfma_f32_32x32x16_f16 a[224:239], v[124:127], v[156:159], a[224:239]
	s_waitcnt lgkmcnt(6)
	v_mfma_f32_32x32x16_f16 a[240:255], v[124:127], v[164:167], a[240:255]
	v_mfma_f32_32x32x16_f16 a[96:111], v[124:127], v[172:175], a[96:111]
	s_waitcnt lgkmcnt(0)
	s_barrier
	ds_read_b128 v[50:53], v40 offset:4608
	ds_read_b128 v[128:131], v49 offset:36864
	v_mfma_f32_32x32x16_f16 a[112:127], v[124:127], v[180:183], a[112:127]
	ds_read_b128 v[168:171], v49 offset:41472
	ds_read_b128 v[136:139], v49 offset:46080
	ds_read_b128 v[176:179], v49 offset:50688
	v_mfma_f32_32x32x16_f16 a[192:207], v[132:135], v[156:159], a[192:207]
	ds_read_b128 v[144:147], v40
	ds_read_b128 v[152:155], v40 offset:9216
	ds_read_b128 v[160:163], v40 offset:13824
	v_mfma_f32_32x32x16_f16 a[208:223], v[132:135], v[164:167], a[208:223]
	v_mfma_f32_32x32x16_f16 a[64:79], v[132:135], v[172:175], a[64:79]
	v_mfma_f32_32x32x16_f16 a[80:95], v[132:135], v[180:183], a[80:95]
	v_mfma_f32_32x32x16_f16 a[160:175], v[140:143], v[156:159], a[160:175]
	v_mfma_f32_32x32x16_f16 a[176:191], v[140:143], v[164:167], a[176:191]
	v_mfma_f32_32x32x16_f16 a[32:47], v[140:143], v[172:175], a[32:47]
	v_mfma_f32_32x32x16_f16 a[48:63], v[140:143], v[180:183], a[48:63]
	v_mfma_f32_32x32x16_f16 a[128:143], v[148:151], v[156:159], a[128:143]
	v_mfma_f32_32x32x16_f16 a[144:159], v[148:151], v[164:167], a[144:159]
	v_mfma_f32_32x32x16_f16 a[16:31], v[148:151], v[172:175], a[16:31]
	v_mfma_f32_32x32x16_f16 a[0:15], v[148:151], v[180:183], a[0:15]
	s_add_i32 s9, s9, 64
	s_cmp_lg_u32 s3, 16
	s_mov_b32 s2, s3
	s_cbranch_scc1 .LBB0_343
	s_waitcnt lgkmcnt(0)
	s_add_i32 s45, s45, 1
	s_cmp_ge_i32 s45, s41
	s_mov_b32 s46, s8
	s_mov_b32 s47, s48
	s_cbranch_scc1 .LBB0_350
	s_mov_b64 s[2:3], -1
	s_and_b64 vcc, exec, s[22:23]
	s_cbranch_vccz .LBB0_347
	v_readlane_b32 s12, v253, 2
	v_readlane_b32 s14, v253, 4
	s_mul_i32 s2, s45, s14
	s_add_i32 s2, s2, s54
	v_readlane_b32 s13, v253, 3
	v_readlane_b32 s15, v253, 5
	s_and_b32 s46, s2, 63
	s_ashr_i32 s47, s2, 6
	s_mov_b64 s[2:3], 0

.Ltpb_7:
	s_cmp_eq_u32 s3, 7
	s_cbranch_scc0 .Ltpb_27
	s_add_i32 s2, s2, -48
	s_branch .Ltpb_done
.Ltpb_27:
	s_cmp_eq_u32 s3, 27
	s_cbranch_scc0 .Ltpb_30
	s_add_i32 s2, s2, 24
	s_branch .Ltpb_done
.Ltpb_30:
	s_cmp_eq_u32 s3, 30
	s_cbranch_scc0 .Ltpb_done
	s_add_i32 s2, s2, -24

.LBB0_350:
	v_readfirstlane_b32 s2, v30
	s_lshr_b32 s2, s2, 7
	s_lshl_b32 s3, s48, 1
	s_add_i32 s3, s3, s2
	s_mov_b32 s6, 0xfe3c0ff0
	s_mov_b32 s7, 0xfffffef
	s_lshr_b64 s[6:7], s[6:7], s3
	s_bitcmp1_b32 s6, 0
	s_cbranch_scc0 .Lep_slow
	s_lshl_b32 s3, s3, 1
	s_mov_b32 s28, 0x3e000000
	s_mov_b32 s29, 1.0
	s_add_i32 s2, s3, 0
	s_cmp_ge_u32 s2, 0x4a
	s_cselect_b32 s18, 2, 0
	s_sub_i32 s6, s2, 16
	s_cmp_lt_u32 s6, 8
	s_cselect_b32 s18, 1, s18
	s_sub_i32 s6, s2, 36
	s_cmp_lt_u32 s6, 8
	s_cselect_b32 s18, 1, s18
	s_sub_i32 s6, s2, 65
	s_cmp_lt_u32 s6, 8
	s_cselect_b32 s18, 1, s18
	s_sub_i32 s6, s2, 49
	s_cmp_lt_u32 s6, 4
	s_cselect_b32 s10, s28, s29
	s_mov_b32 s11, s10
	s_add_i32 s2, s3, 1
	s_cmp_ge_u32 s2, 0x4a
	s_cselect_b32 s19, 2, 0
	s_sub_i32 s6, s2, 16
	s_cmp_lt_u32 s6, 8
	s_cselect_b32 s19, 1, s19
	s_sub_i32 s6, s2, 36
	s_cmp_lt_u32 s6, 8
	s_cselect_b32 s19, 1, s19
	s_sub_i32 s6, s2, 65
	s_cmp_lt_u32 s6, 8
	s_cselect_b32 s19, 1, s19
	s_sub_i32 s6, s2, 49
	s_cmp_lt_u32 s6, 4
	s_cselect_b32 s26, s28, s29
	s_mov_b32 s27, s26
	s_mov_b32 s12, 0x1e800
	s_mov_b32 s13, 0
	s_movk_i32 s14, 0x80
	s_mov_b32 s15, 0
	s_mov_b32 s16, 0xbfb8aa3b
	s_mov_b32 s17, s16
	s_lshl_b32 s50, s8, 8
	s_lshl_b32 s6, s48, 8
	v_add_u32_e32 v184, s50, v46
	v_or3_b32 v2, s6, v30, v31
	v_mov_b32_e32 v3, 0
	v_lshl_add_u64 v[4:5], v[2:3], 1, s[56:57]
	v_mad_u64_u32 v[178:179], s[6:7], v184, s68, v[4:5]
	v_mov_b64_e32 v[172:173], v[178:179]
	s_mov_b32 s51, s18
	ds_write_b32 v32, a224
	ds_write_b32 v33, a240
	ds_write_b32 v32, a225 offset:272
	ds_write_b32 v33, a241 offset:272
	ds_write_b32 v32, a226 offset:544
	ds_write_b32 v33, a242 offset:544
	ds_write_b32 v32, a227 offset:816
	ds_write_b32 v33, a243 offset:816
	ds_write_b32 v32, a228 offset:2176
	ds_write_b32 v33, a244 offset:2176
	ds_write_b32 v32, a229 offset:2448
	ds_write_b32 v33, a245 offset:2448
	ds_write_b32 v32, a230 offset:2720
	ds_write_b32 v33, a246 offset:2720
	ds_write_b32 v32, a231 offset:2992
	ds_write_b32 v33, a247 offset:2992
	ds_write_b32 v32, a232 offset:4352
	ds_write_b32 v33, a248 offset:4352
	ds_write_b32 v32, a233 offset:4624
	ds_write_b32 v33, a249 offset:4624
	ds_write_b32 v32, a234 offset:4896
	ds_write_b32 v33, a250 offset:4896
	ds_write_b32 v32, a235 offset:5168
	ds_write_b32 v33, a251 offset:5168
	ds_write_b32 v32, a236 offset:6528
	ds_write_b32 v33, a252 offset:6528
	ds_write_b32 v32, a237 offset:6800
	ds_write_b32 v33, a253 offset:6800
	ds_write_b32 v32, a238 offset:7072
	ds_write_b32 v33, a254 offset:7072
	ds_write_b32 v32, a239 offset:7344
	ds_write_b32 v33, a255 offset:7344
	ds_read_b128 v[124:127], v48
	ds_read_b128 v[128:131], v48 offset:16
	ds_read_b128 v[132:135], v48 offset:2176
	ds_read_b128 v[136:139], v48 offset:2192
	ds_read_b128 v[140:143], v48 offset:4352
	ds_read_b128 v[144:147], v48 offset:4368
	ds_read_b128 v[148:151], v48 offset:6528
	ds_read_b128 v[152:155], v48 offset:6544
	s_movk_i32 s49, 1
	s_branch .Lep_compute
.Lep_p1:
	ds_write_b32 v32, a192
	ds_write_b32 v33, a208
	ds_write_b32 v32, a193 offset:272
	ds_write_b32 v33, a209 offset:272
	ds_write_b32 v32, a194 offset:544
	ds_write_b32 v33, a210 offset:544
	ds_write_b32 v32, a195 offset:816
	ds_write_b32 v33, a211 offset:816
	ds_write_b32 v32, a196 offset:2176
	ds_write_b32 v33, a212 offset:2176
	ds_write_b32 v32, a197 offset:2448
	ds_write_b32 v33, a213 offset:2448
	ds_write_b32 v32, a198 offset:2720
	ds_write_b32 v33, a214 offset:2720
	ds_write_b32 v32, a199 offset:2992
	ds_write_b32 v33, a215 offset:2992
	ds_write_b32 v32, a200 offset:4352
	ds_write_b32 v33, a216 offset:4352
	ds_write_b32 v32, a201 offset:4624
	ds_write_b32 v33, a217 offset:4624
	ds_write_b32 v32, a202 offset:4896
	ds_write_b32 v33, a218 offset:4896
	ds_write_b32 v32, a203 offset:5168
	ds_write_b32 v33, a219 offset:5168
	ds_write_b32 v32, a204 offset:6528
	ds_write_b32 v33, a220 offset:6528
	ds_write_b32 v32, a205 offset:6800
	ds_write_b32 v33, a221 offset:6800
	ds_write_b32 v32, a206 offset:7072
	ds_write_b32 v33, a222 offset:7072
	ds_write_b32 v32, a207 offset:7344
	ds_write_b32 v33, a223 offset:7344
	ds_read_b128 v[124:127], v48
	ds_read_b128 v[128:131], v48 offset:16
	ds_read_b128 v[132:135], v48 offset:2176
	ds_read_b128 v[136:139], v48 offset:2192
	ds_read_b128 v[140:143], v48 offset:4352
	ds_read_b128 v[144:147], v48 offset:4368
	ds_read_b128 v[148:151], v48 offset:6528
	ds_read_b128 v[152:155], v48 offset:6544
	s_movk_i32 s49, 2
	s_branch .Lep_compute
.Lep_p2:
	ds_write_b32 v32, a160
	ds_write_b32 v33, a176
	ds_write_b32 v32, a161 offset:272
	ds_write_b32 v33, a177 offset:272
	ds_write_b32 v32, a162 offset:544
	ds_write_b32 v33, a178 offset:544
	ds_write_b32 v32, a163 offset:816
	ds_write_b32 v33, a179 offset:816
	ds_write_b32 v32, a164 offset:2176
	ds_write_b32 v33, a180 offset:2176
	ds_write_b32 v32, a165 offset:2448
	ds_write_b32 v33, a181 offset:2448
	ds_write_b32 v32, a166 offset:2720
	ds_write_b32 v33, a182 offset:2720
	ds_write_b32 v32, a167 offset:2992
	ds_write_b32 v33, a183 offset:2992
	ds_write_b32 v32, a168 offset:4352
	ds_write_b32 v33, a184 offset:4352
	ds_write_b32 v32, a169 offset:4624
	ds_write_b32 v33, a185 offset:4624
	ds_write_b32 v32, a170 offset:4896
	ds_write_b32 v33, a186 offset:4896
	ds_write_b32 v32, a171 offset:5168
	ds_write_b32 v33, a187 offset:5168
	ds_write_b32 v32, a172 offset:6528
	ds_write_b32 v33, a188 offset:6528
	ds_write_b32 v32, a173 offset:6800
	ds_write_b32 v33, a189 offset:6800
	ds_write_b32 v32, a174 offset:7072
	ds_write_b32 v33, a190 offset:7072
	ds_write_b32 v32, a175 offset:7344
	ds_write_b32 v33, a191 offset:7344
	ds_read_b128 v[124:127], v48
	ds_read_b128 v[128:131], v48 offset:16
	ds_read_b128 v[132:135], v48 offset:2176
	ds_read_b128 v[136:139], v48 offset:2192
	ds_read_b128 v[140:143], v48 offset:4352
	ds_read_b128 v[144:147], v48 offset:4368
	ds_read_b128 v[148:151], v48 offset:6528
	ds_read_b128 v[152:155], v48 offset:6544
	s_movk_i32 s49, 3
	s_branch .Lep_compute
.Lep_p3:
	ds_write_b32 v32, a128
	ds_write_b32 v33, a144
	ds_write_b32 v32, a129 offset:272
	ds_write_b32 v33, a145 offset:272
	ds_write_b32 v32, a130 offset:544
	ds_write_b32 v33, a146 offset:544
	ds_write_b32 v32, a131 offset:816
	ds_write_b32 v33, a147 offset:816
	ds_write_b32 v32, a132 offset:2176
	ds_write_b32 v33, a148 offset:2176
	ds_write_b32 v32, a133 offset:2448
	ds_write_b32 v33, a149 offset:2448
	ds_write_b32 v32, a134 offset:2720
	ds_write_b32 v33, a150 offset:2720
	ds_write_b32 v32, a135 offset:2992
	ds_write_b32 v33, a151 offset:2992
	ds_write_b32 v32, a136 offset:4352
	ds_write_b32 v33, a152 offset:4352
	ds_write_b32 v32, a137 offset:4624
	ds_write_b32 v33, a153 offset:4624
	ds_write_b32 v32, a138 offset:4896
	ds_write_b32 v33, a154 offset:4896
	ds_write_b32 v32, a139 offset:5168
	ds_write_b32 v33, a155 offset:5168
	ds_write_b32 v32, a140 offset:6528
	ds_write_b32 v33, a156 offset:6528
	ds_write_b32 v32, a141 offset:6800
	ds_write_b32 v33, a157 offset:6800
	ds_write_b32 v32, a142 offset:7072
	ds_write_b32 v33, a158 offset:7072
	ds_write_b32 v32, a143 offset:7344
	ds_write_b32 v33, a159 offset:7344
	ds_read_b128 v[124:127], v48
	ds_read_b128 v[128:131], v48 offset:16
	ds_read_b128 v[132:135], v48 offset:2176
	ds_read_b128 v[136:139], v48 offset:2192
	ds_read_b128 v[140:143], v48 offset:4352
	ds_read_b128 v[144:147], v48 offset:4368
	ds_read_b128 v[148:151], v48 offset:6528
	ds_read_b128 v[152:155], v48 offset:6544
	s_movk_i32 s49, 4
	s_branch .Lep_compute
.Lep_p4:
	s_mov_b32 s51, s19
	s_mov_b64 s[10:11], s[26:27]
	v_lshl_add_u64 v[172:173], v[178:179], 0, s[14:15]
	ds_write_b32 v32, a96
	ds_write_b32 v33, a112
	ds_write_b32 v32, a97 offset:272
	ds_write_b32 v33, a113 offset:272
	ds_write_b32 v32, a98 offset:544
	ds_write_b32 v33, a114 offset:544
	ds_write_b32 v32, a99 offset:816
	ds_write_b32 v33, a115 offset:816
	ds_write_b32 v32, a100 offset:2176
	ds_write_b32 v33, a116 offset:2176
	ds_write_b32 v32, a101 offset:2448
	ds_write_b32 v33, a117 offset:2448
	ds_write_b32 v32, a102 offset:2720
	ds_write_b32 v33, a118 offset:2720
	ds_write_b32 v32, a103 offset:2992
	ds_write_b32 v33, a119 offset:2992
	ds_write_b32 v32, a104 offset:4352
	ds_write_b32 v33, a120 offset:4352
	ds_write_b32 v32, a105 offset:4624
	ds_write_b32 v33, a121 offset:4624
	ds_write_b32 v32, a106 offset:4896
	ds_write_b32 v33, a122 offset:4896
	ds_write_b32 v32, a107 offset:5168
	ds_write_b32 v33, a123 offset:5168
	ds_write_b32 v32, a108 offset:6528
	ds_write_b32 v33, a124 offset:6528
	ds_write_b32 v32, a109 offset:6800
	ds_write_b32 v33, a125 offset:6800
	ds_write_b32 v32, a110 offset:7072
	ds_write_b32 v33, a126 offset:7072
	ds_write_b32 v32, a111 offset:7344
	ds_write_b32 v33, a127 offset:7344
	ds_read_b128 v[124:127], v48
	ds_read_b128 v[128:131], v48 offset:16
	ds_read_b128 v[132:135], v48 offset:2176
	ds_read_b128 v[136:139], v48 offset:2192
	ds_read_b128 v[140:143], v48 offset:4352
	ds_read_b128 v[144:147], v48 offset:4368
	ds_read_b128 v[148:151], v48 offset:6528
	ds_read_b128 v[152:155], v48 offset:6544
	s_movk_i32 s49, 5
	s_branch .Lep_compute
.Lep_p5:
	ds_write_b32 v32, a64
	ds_write_b32 v33, a80
	ds_write_b32 v32, a65 offset:272
	ds_write_b32 v33, a81 offset:272
	ds_write_b32 v32, a66 offset:544
	ds_write_b32 v33, a82 offset:544
	ds_write_b32 v32, a67 offset:816
	ds_write_b32 v33, a83 offset:816
	ds_write_b32 v32, a68 offset:2176
	ds_write_b32 v33, a84 offset:2176
	ds_write_b32 v32, a69 offset:2448
	ds_write_b32 v33, a85 offset:2448
	ds_write_b32 v32, a70 offset:2720
	ds_write_b32 v33, a86 offset:2720
	ds_write_b32 v32, a71 offset:2992
	ds_write_b32 v33, a87 offset:2992
	ds_write_b32 v32, a72 offset:4352
	ds_write_b32 v33, a88 offset:4352
	ds_write_b32 v32, a73 offset:4624
	ds_write_b32 v33, a89 offset:4624
	ds_write_b32 v32, a74 offset:4896
	ds_write_b32 v33, a90 offset:4896
	ds_write_b32 v32, a75 offset:5168
	ds_write_b32 v33, a91 offset:5168
	ds_write_b32 v32, a76 offset:6528
	ds_write_b32 v33, a92 offset:6528
	ds_write_b32 v32, a77 offset:6800
	ds_write_b32 v33, a93 offset:6800
	ds_write_b32 v32, a78 offset:7072
	ds_write_b32 v33, a94 offset:7072
	ds_write_b32 v32, a79 offset:7344
	ds_write_b32 v33, a95 offset:7344
	ds_read_b128 v[124:127], v48
	ds_read_b128 v[128:131], v48 offset:16
	ds_read_b128 v[132:135], v48 offset:2176
	ds_read_b128 v[136:139], v48 offset:2192
	ds_read_b128 v[140:143], v48 offset:4352
	ds_read_b128 v[144:147], v48 offset:4368
	ds_read_b128 v[148:151], v48 offset:6528
	ds_read_b128 v[152:155], v48 offset:6544
	s_movk_i32 s49, 6
	s_branch .Lep_compute
.Lep_p6:
	ds_write_b32 v32, a32
	ds_write_b32 v33, a48
	ds_write_b32 v32, a33 offset:272
	ds_write_b32 v33, a49 offset:272
	ds_write_b32 v32, a34 offset:544
	ds_write_b32 v33, a50 offset:544
	ds_write_b32 v32, a35 offset:816
	ds_write_b32 v33, a51 offset:816
	ds_write_b32 v32, a36 offset:2176
	ds_write_b32 v33, a52 offset:2176
	ds_write_b32 v32, a37 offset:2448
	ds_write_b32 v33, a53 offset:2448
	ds_write_b32 v32, a38 offset:2720
	ds_write_b32 v33, a54 offset:2720
	ds_write_b32 v32, a39 offset:2992
	ds_write_b32 v33, a55 offset:2992
	ds_write_b32 v32, a40 offset:4352
	ds_write_b32 v33, a56 offset:4352
	ds_write_b32 v32, a41 offset:4624
	ds_write_b32 v33, a57 offset:4624
	ds_write_b32 v32, a42 offset:4896
	ds_write_b32 v33, a58 offset:4896
	ds_write_b32 v32, a43 offset:5168
	ds_write_b32 v33, a59 offset:5168
	ds_write_b32 v32, a44 offset:6528
	ds_write_b32 v33, a60 offset:6528
	ds_write_b32 v32, a45 offset:6800
	ds_write_b32 v33, a61 offset:6800
	ds_write_b32 v32, a46 offset:7072
	ds_write_b32 v33, a62 offset:7072
	ds_write_b32 v32, a47 offset:7344
	ds_write_b32 v33, a63 offset:7344
	ds_read_b128 v[124:127], v48
	ds_read_b128 v[128:131], v48 offset:16
	ds_read_b128 v[132:135], v48 offset:2176
	ds_read_b128 v[136:139], v48 offset:2192
	ds_read_b128 v[140:143], v48 offset:4352
	ds_read_b128 v[144:147], v48 offset:4368
	ds_read_b128 v[148:151], v48 offset:6528
	ds_read_b128 v[152:155], v48 offset:6544
	s_movk_i32 s49, 7
	s_branch .Lep_compute
.Lep_p7:
	ds_write_b32 v32, a16
	ds_write_b32 v33, a0
	ds_write_b32 v32, a17 offset:272
	ds_write_b32 v33, a1 offset:272
	ds_write_b32 v32, a18 offset:544
	ds_write_b32 v33, a2 offset:544
	ds_write_b32 v32, a19 offset:816
	ds_write_b32 v33, a3 offset:816
	ds_write_b32 v32, a20 offset:2176
	ds_write_b32 v33, a4 offset:2176
	ds_write_b32 v32, a21 offset:2448
	ds_write_b32 v33, a5 offset:2448
	ds_write_b32 v32, a22 offset:2720
	ds_write_b32 v33, a6 offset:2720
	ds_write_b32 v32, a23 offset:2992
	ds_write_b32 v33, a7 offset:2992
	ds_write_b32 v32, a24 offset:4352
	ds_write_b32 v33, a8 offset:4352
	ds_write_b32 v32, a25 offset:4624
	ds_write_b32 v33, a9 offset:4624
	ds_write_b32 v32, a26 offset:4896
	ds_write_b32 v33, a10 offset:4896
	ds_write_b32 v32, a27 offset:5168
	ds_write_b32 v33, a11 offset:5168
	ds_write_b32 v32, a28 offset:6528
	ds_write_b32 v33, a12 offset:6528
	ds_write_b32 v32, a29 offset:6800
	ds_write_b32 v33, a13 offset:6800
	ds_write_b32 v32, a30 offset:7072
	ds_write_b32 v33, a14 offset:7072
	ds_write_b32 v32, a31 offset:7344
	ds_write_b32 v33, a15 offset:7344
	ds_read_b128 v[124:127], v48
	ds_read_b128 v[128:131], v48 offset:16
	ds_read_b128 v[132:135], v48 offset:2176
	ds_read_b128 v[136:139], v48 offset:2192
	ds_read_b128 v[140:143], v48 offset:4352
	ds_read_b128 v[144:147], v48 offset:4368
	ds_read_b128 v[148:151], v48 offset:6528
	ds_read_b128 v[152:155], v48 offset:6544
	s_movk_i32 s49, 8
	s_branch .Lep_compute
.Lep_compute:
	s_cmp_eq_u32 s51, 2
	s_cbranch_scc1 .Lep_sigm
	s_cmp_eq_u32 s51, 1
	s_cbranch_scc1 .Lep_silu
	s_waitcnt lgkmcnt(6)
	v_pk_mul_f32 v[156:157], v[124:125], s[10:11]
	v_pk_mul_f32 v[158:159], v[126:127], s[10:11]
	v_pk_mul_f32 v[160:161], v[128:129], s[10:11]
	v_pk_mul_f32 v[162:163], v[130:131], s[10:11]
	v_cvt_pk_f16_f32 v174, v156, v157
	v_cvt_pk_f16_f32 v175, v158, v159
	v_cvt_pk_f16_f32 v176, v160, v161
	v_cvt_pk_f16_f32 v177, v162, v163
	global_store_dwordx4 v[172:173], v[174:177], off nt
	v_lshl_add_u64 v[172:173], v[172:173], 0, s[12:13]
	s_waitcnt lgkmcnt(4)
	v_pk_mul_f32 v[164:165], v[132:133], s[10:11]
	v_pk_mul_f32 v[166:167], v[134:135], s[10:11]
	v_pk_mul_f32 v[168:169], v[136:137], s[10:11]
	v_pk_mul_f32 v[170:171], v[138:139], s[10:11]
	v_cvt_pk_f16_f32 v180, v164, v165
	v_cvt_pk_f16_f32 v181, v166, v167
	v_cvt_pk_f16_f32 v182, v168, v169
	v_cvt_pk_f16_f32 v183, v170, v171
	global_store_dwordx4 v[172:173], v[180:183], off nt
	v_lshl_add_u64 v[172:173], v[172:173], 0, s[12:13]
	s_waitcnt lgkmcnt(2)
	v_pk_mul_f32 v[156:157], v[140:141], s[10:11]
	v_pk_mul_f32 v[158:159], v[142:143], s[10:11]
	v_pk_mul_f32 v[160:161], v[144:145], s[10:11]
	v_pk_mul_f32 v[162:163], v[146:147], s[10:11]
	v_cvt_pk_f16_f32 v174, v156, v157
	v_cvt_pk_f16_f32 v175, v158, v159
	v_cvt_pk_f16_f32 v176, v160, v161
	v_cvt_pk_f16_f32 v177, v162, v163
	global_store_dwordx4 v[172:173], v[174:177], off nt
	v_lshl_add_u64 v[172:173], v[172:173], 0, s[12:13]
	s_waitcnt lgkmcnt(0)
	v_pk_mul_f32 v[164:165], v[148:149], s[10:11]
	v_pk_mul_f32 v[166:167], v[150:151], s[10:11]
	v_pk_mul_f32 v[168:169], v[152:153], s[10:11]
	v_pk_mul_f32 v[170:171], v[154:155], s[10:11]
	v_cvt_pk_f16_f32 v180, v164, v165
	v_cvt_pk_f16_f32 v181, v166, v167
	v_cvt_pk_f16_f32 v182, v168, v169
	v_cvt_pk_f16_f32 v183, v170, v171
	global_store_dwordx4 v[172:173], v[180:183], off nt
	v_lshl_add_u64 v[172:173], v[172:173], 0, s[12:13]
	s_branch .Lep_ret
.Lep_silu:
	s_waitcnt lgkmcnt(6)
	v_pk_mul_f32 v[156:157], v[124:125], s[16:17]
	v_pk_mul_f32 v[158:159], v[126:127], s[16:17]
	v_pk_mul_f32 v[160:161], v[128:129], s[16:17]
	v_pk_mul_f32 v[162:163], v[130:131], s[16:17]
	v_exp_f32_e32 v156, v156
	v_exp_f32_e32 v157, v157
	v_exp_f32_e32 v158, v158
	v_exp_f32_e32 v159, v159
	v_pk_add_f32 v[156:157], v[156:157], 1.0 op_sel_hi:[1,0]
	v_exp_f32_e32 v160, v160
	v_exp_f32_e32 v161, v161
	v_pk_add_f32 v[158:159], v[158:159], 1.0 op_sel_hi:[1,0]
	v_exp_f32_e32 v162, v162
	v_exp_f32_e32 v163, v163
	v_rcp_f32_e32 v156, v156
	v_rcp_f32_e32 v157, v157
	v_pk_add_f32 v[160:161], v[160:161], 1.0 op_sel_hi:[1,0]
	v_rcp_f32_e32 v158, v158
	v_rcp_f32_e32 v159, v159
	v_pk_add_f32 v[162:163], v[162:163], 1.0 op_sel_hi:[1,0]
	v_rcp_f32_e32 v160, v160
	v_rcp_f32_e32 v161, v161
	v_pk_mul_f32 v[156:157], v[156:157], v[124:125]
	v_rcp_f32_e32 v162, v162
	v_pk_mul_f32 v[158:159], v[158:159], v[126:127]
	v_rcp_f32_e32 v163, v163
	v_pk_mul_f32 v[160:161], v[160:161], v[128:129]
	v_pk_mul_f32 v[162:163], v[162:163], v[130:131]
	v_cvt_pk_f16_f32 v174, v156, v157
	v_cvt_pk_f16_f32 v175, v158, v159
	v_cvt_pk_f16_f32 v176, v160, v161
	v_cvt_pk_f16_f32 v177, v162, v163
	global_store_dwordx4 v[172:173], v[174:177], off nt
	v_lshl_add_u64 v[172:173], v[172:173], 0, s[12:13]
	s_waitcnt lgkmcnt(4)
	v_pk_mul_f32 v[164:165], v[132:133], s[16:17]
	v_pk_mul_f32 v[166:167], v[134:135], s[16:17]
	v_pk_mul_f32 v[168:169], v[136:137], s[16:17]
	v_pk_mul_f32 v[170:171], v[138:139], s[16:17]
	v_exp_f32_e32 v164, v164
	v_exp_f32_e32 v165, v165
	v_exp_f32_e32 v166, v166
	v_exp_f32_e32 v167, v167
	v_pk_add_f32 v[164:165], v[164:165], 1.0 op_sel_hi:[1,0]
	v_exp_f32_e32 v168, v168
	v_exp_f32_e32 v169, v169
	v_pk_add_f32 v[166:167], v[166:167], 1.0 op_sel_hi:[1,0]
	v_exp_f32_e32 v170, v170
	v_exp_f32_e32 v171, v171
	v_rcp_f32_e32 v164, v164
	v_rcp_f32_e32 v165, v165
	v_pk_add_f32 v[168:169], v[168:169], 1.0 op_sel_hi:[1,0]
	v_rcp_f32_e32 v166, v166
	v_rcp_f32_e32 v167, v167
	v_pk_add_f32 v[170:171], v[170:171], 1.0 op_sel_hi:[1,0]
	v_rcp_f32_e32 v168, v168
	v_rcp_f32_e32 v169, v169
	v_pk_mul_f32 v[164:165], v[164:165], v[132:133]
	v_rcp_f32_e32 v170, v170
	v_pk_mul_f32 v[166:167], v[166:167], v[134:135]
	v_rcp_f32_e32 v171, v171
	v_pk_mul_f32 v[168:169], v[168:169], v[136:137]
	v_pk_mul_f32 v[170:171], v[170:171], v[138:139]
	v_cvt_pk_f16_f32 v180, v164, v165
	v_cvt_pk_f16_f32 v181, v166, v167
	v_cvt_pk_f16_f32 v182, v168, v169
	v_cvt_pk_f16_f32 v183, v170, v171
	global_store_dwordx4 v[172:173], v[180:183], off nt
	v_lshl_add_u64 v[172:173], v[172:173], 0, s[12:13]
	s_waitcnt lgkmcnt(2)
	v_pk_mul_f32 v[156:157], v[140:141], s[16:17]
	v_pk_mul_f32 v[158:159], v[142:143], s[16:17]
	v_pk_mul_f32 v[160:161], v[144:145], s[16:17]
	v_pk_mul_f32 v[162:163], v[146:147], s[16:17]
	v_exp_f32_e32 v156, v156
	v_exp_f32_e32 v157, v157
	v_exp_f32_e32 v158, v158
	v_exp_f32_e32 v159, v159
	v_pk_add_f32 v[156:157], v[156:157], 1.0 op_sel_hi:[1,0]
	v_exp_f32_e32 v160, v160
	v_exp_f32_e32 v161, v161
	v_pk_add_f32 v[158:159], v[158:159], 1.0 op_sel_hi:[1,0]
	v_exp_f32_e32 v162, v162
	v_exp_f32_e32 v163, v163
	v_rcp_f32_e32 v156, v156
	v_rcp_f32_e32 v157, v157
	v_pk_add_f32 v[160:161], v[160:161], 1.0 op_sel_hi:[1,0]
	v_rcp_f32_e32 v158, v158
	v_rcp_f32_e32 v159, v159
	v_pk_add_f32 v[162:163], v[162:163], 1.0 op_sel_hi:[1,0]
	v_rcp_f32_e32 v160, v160
	v_rcp_f32_e32 v161, v161
	v_pk_mul_f32 v[156:157], v[156:157], v[140:141]
	v_rcp_f32_e32 v162, v162
	v_pk_mul_f32 v[158:159], v[158:159], v[142:143]
	v_rcp_f32_e32 v163, v163
	v_pk_mul_f32 v[160:161], v[160:161], v[144:145]
	v_pk_mul_f32 v[162:163], v[162:163], v[146:147]
	v_cvt_pk_f16_f32 v174, v156, v157
	v_cvt_pk_f16_f32 v175, v158, v159
	v_cvt_pk_f16_f32 v176, v160, v161
	v_cvt_pk_f16_f32 v177, v162, v163
	global_store_dwordx4 v[172:173], v[174:177], off nt
	v_lshl_add_u64 v[172:173], v[172:173], 0, s[12:13]
	s_waitcnt lgkmcnt(0)
	v_pk_mul_f32 v[164:165], v[148:149], s[16:17]
	v_pk_mul_f32 v[166:167], v[150:151], s[16:17]
	v_pk_mul_f32 v[168:169], v[152:153], s[16:17]
	v_pk_mul_f32 v[170:171], v[154:155], s[16:17]
	v_exp_f32_e32 v164, v164
	v_exp_f32_e32 v165, v165
	v_exp_f32_e32 v166, v166
	v_exp_f32_e32 v167, v167
	v_pk_add_f32 v[164:165], v[164:165], 1.0 op_sel_hi:[1,0]
	v_exp_f32_e32 v168, v168
	v_exp_f32_e32 v169, v169
	v_pk_add_f32 v[166:167], v[166:167], 1.0 op_sel_hi:[1,0]
	v_exp_f32_e32 v170, v170
	v_exp_f32_e32 v171, v171
	v_rcp_f32_e32 v164, v164
	v_rcp_f32_e32 v165, v165
	v_pk_add_f32 v[168:169], v[168:169], 1.0 op_sel_hi:[1,0]
	v_rcp_f32_e32 v166, v166
	v_rcp_f32_e32 v167, v167
	v_pk_add_f32 v[170:171], v[170:171], 1.0 op_sel_hi:[1,0]
	v_rcp_f32_e32 v168, v168
	v_rcp_f32_e32 v169, v169
	v_pk_mul_f32 v[164:165], v[164:165], v[148:149]
	v_rcp_f32_e32 v170, v170
	v_pk_mul_f32 v[166:167], v[166:167], v[150:151]
	v_rcp_f32_e32 v171, v171
	v_pk_mul_f32 v[168:169], v[168:169], v[152:153]
	v_pk_mul_f32 v[170:171], v[170:171], v[154:155]
	v_cvt_pk_f16_f32 v180, v164, v165
	v_cvt_pk_f16_f32 v181, v166, v167
	v_cvt_pk_f16_f32 v182, v168, v169
	v_cvt_pk_f16_f32 v183, v170, v171
	global_store_dwordx4 v[172:173], v[180:183], off nt
	v_lshl_add_u64 v[172:173], v[172:173], 0, s[12:13]
	s_branch .Lep_ret
.Lep_sigm:
	s_waitcnt lgkmcnt(6)
	v_pk_mul_f32 v[156:157], v[124:125], s[16:17]
	v_pk_mul_f32 v[158:159], v[126:127], s[16:17]
	v_pk_mul_f32 v[160:161], v[128:129], s[16:17]
	v_pk_mul_f32 v[162:163], v[130:131], s[16:17]
	v_exp_f32_e32 v156, v156
	v_exp_f32_e32 v157, v157
	v_exp_f32_e32 v158, v158
	v_exp_f32_e32 v159, v159
	v_pk_add_f32 v[156:157], v[156:157], 1.0 op_sel_hi:[1,0]
	v_exp_f32_e32 v160, v160
	v_exp_f32_e32 v161, v161
	v_pk_add_f32 v[158:159], v[158:159], 1.0 op_sel_hi:[1,0]
	v_exp_f32_e32 v162, v162
	v_exp_f32_e32 v163, v163
	v_rcp_f32_e32 v156, v156
	v_rcp_f32_e32 v157, v157
	v_pk_add_f32 v[160:161], v[160:161], 1.0 op_sel_hi:[1,0]
	v_rcp_f32_e32 v158, v158
	v_rcp_f32_e32 v159, v159
	v_pk_add_f32 v[162:163], v[162:163], 1.0 op_sel_hi:[1,0]
	v_rcp_f32_e32 v160, v160
	v_rcp_f32_e32 v161, v161
	v_rcp_f32_e32 v162, v162
	v_rcp_f32_e32 v163, v163
	v_cvt_pk_f16_f32 v174, v156, v157
	v_cvt_pk_f16_f32 v175, v158, v159
	v_cvt_pk_f16_f32 v176, v160, v161
	v_cvt_pk_f16_f32 v177, v162, v163
	global_store_dwordx4 v[172:173], v[174:177], off nt
	v_lshl_add_u64 v[172:173], v[172:173], 0, s[12:13]
	s_waitcnt lgkmcnt(4)
	v_pk_mul_f32 v[164:165], v[132:133], s[16:17]
	v_pk_mul_f32 v[166:167], v[134:135], s[16:17]
	v_pk_mul_f32 v[168:169], v[136:137], s[16:17]
	v_pk_mul_f32 v[170:171], v[138:139], s[16:17]
	v_exp_f32_e32 v164, v164
	v_exp_f32_e32 v165, v165
	v_exp_f32_e32 v166, v166
	v_exp_f32_e32 v167, v167
	v_pk_add_f32 v[164:165], v[164:165], 1.0 op_sel_hi:[1,0]
	v_exp_f32_e32 v168, v168
	v_exp_f32_e32 v169, v169
	v_pk_add_f32 v[166:167], v[166:167], 1.0 op_sel_hi:[1,0]
	v_exp_f32_e32 v170, v170
	v_exp_f32_e32 v171, v171
	v_rcp_f32_e32 v164, v164
	v_rcp_f32_e32 v165, v165
	v_pk_add_f32 v[168:169], v[168:169], 1.0 op_sel_hi:[1,0]
	v_rcp_f32_e32 v166, v166
	v_rcp_f32_e32 v167, v167
	v_pk_add_f32 v[170:171], v[170:171], 1.0 op_sel_hi:[1,0]
	v_rcp_f32_e32 v168, v168
	v_rcp_f32_e32 v169, v169
	v_rcp_f32_e32 v170, v170
	v_rcp_f32_e32 v171, v171
	v_cvt_pk_f16_f32 v180, v164, v165
	v_cvt_pk_f16_f32 v181, v166, v167
	v_cvt_pk_f16_f32 v182, v168, v169
	v_cvt_pk_f16_f32 v183, v170, v171
	global_store_dwordx4 v[172:173], v[180:183], off nt
	v_lshl_add_u64 v[172:173], v[172:173], 0, s[12:13]
	s_waitcnt lgkmcnt(2)
	v_pk_mul_f32 v[156:157], v[140:141], s[16:17]
	v_pk_mul_f32 v[158:159], v[142:143], s[16:17]
	v_pk_mul_f32 v[160:161], v[144:145], s[16:17]
	v_pk_mul_f32 v[162:163], v[146:147], s[16:17]
	v_exp_f32_e32 v156, v156
	v_exp_f32_e32 v157, v157
	v_exp_f32_e32 v158, v158
	v_exp_f32_e32 v159, v159
	v_pk_add_f32 v[156:157], v[156:157], 1.0 op_sel_hi:[1,0]
	v_exp_f32_e32 v160, v160
	v_exp_f32_e32 v161, v161
	v_pk_add_f32 v[158:159], v[158:159], 1.0 op_sel_hi:[1,0]
	v_exp_f32_e32 v162, v162
	v_exp_f32_e32 v163, v163
	v_rcp_f32_e32 v156, v156
	v_rcp_f32_e32 v157, v157
	v_pk_add_f32 v[160:161], v[160:161], 1.0 op_sel_hi:[1,0]
	v_rcp_f32_e32 v158, v158
	v_rcp_f32_e32 v159, v159
	v_pk_add_f32 v[162:163], v[162:163], 1.0 op_sel_hi:[1,0]
	v_rcp_f32_e32 v160, v160
	v_rcp_f32_e32 v161, v161
	v_rcp_f32_e32 v162, v162
	v_rcp_f32_e32 v163, v163
	v_cvt_pk_f16_f32 v174, v156, v157
	v_cvt_pk_f16_f32 v175, v158, v159
	v_cvt_pk_f16_f32 v176, v160, v161
	v_cvt_pk_f16_f32 v177, v162, v163
	global_store_dwordx4 v[172:173], v[174:177], off nt
	v_lshl_add_u64 v[172:173], v[172:173], 0, s[12:13]
	s_waitcnt lgkmcnt(0)
	v_pk_mul_f32 v[164:165], v[148:149], s[16:17]
	v_pk_mul_f32 v[166:167], v[150:151], s[16:17]
	v_pk_mul_f32 v[168:169], v[152:153], s[16:17]
	v_pk_mul_f32 v[170:171], v[154:155], s[16:17]
	v_exp_f32_e32 v164, v164
	v_exp_f32_e32 v165, v165
	v_exp_f32_e32 v166, v166
	v_exp_f32_e32 v167, v167
	v_pk_add_f32 v[164:165], v[164:165], 1.0 op_sel_hi:[1,0]
	v_exp_f32_e32 v168, v168
	v_exp_f32_e32 v169, v169
	v_pk_add_f32 v[166:167], v[166:167], 1.0 op_sel_hi:[1,0]
	v_exp_f32_e32 v170, v170
	v_exp_f32_e32 v171, v171
	v_rcp_f32_e32 v164, v164
	v_rcp_f32_e32 v165, v165
	v_pk_add_f32 v[168:169], v[168:169], 1.0 op_sel_hi:[1,0]
	v_rcp_f32_e32 v166, v166
	v_rcp_f32_e32 v167, v167
	v_pk_add_f32 v[170:171], v[170:171], 1.0 op_sel_hi:[1,0]
	v_rcp_f32_e32 v168, v168
	v_rcp_f32_e32 v169, v169
	v_rcp_f32_e32 v170, v170
	v_rcp_f32_e32 v171, v171
	v_cvt_pk_f16_f32 v180, v164, v165
	v_cvt_pk_f16_f32 v181, v166, v167
	v_cvt_pk_f16_f32 v182, v168, v169
	v_cvt_pk_f16_f32 v183, v170, v171
	global_store_dwordx4 v[172:173], v[180:183], off nt
	v_lshl_add_u64 v[172:173], v[172:173], 0, s[12:13]
.Lep_ret:
	s_cmp_eq_u32 s49, 1
	s_cbranch_scc1 .Lep_p1
	s_cmp_eq_u32 s49, 2
	s_cbranch_scc1 .Lep_p2
	s_cmp_eq_u32 s49, 3
	s_cbranch_scc1 .Lep_p3
	s_cmp_eq_u32 s49, 4
	s_cbranch_scc1 .Lep_p4
	s_cmp_eq_u32 s49, 5
	s_cbranch_scc1 .Lep_p5
	s_cmp_eq_u32 s49, 6
	s_cbranch_scc1 .Lep_p6
	s_cmp_eq_u32 s49, 7
	s_cbranch_scc1 .Lep_p7
	s_branch .LBB0_341

.LBB0_356:
	s_or_b64 exec, exec, s[34:35]
	s_andn2_b64 vcc, exec, s[12:13]
	s_cbranch_vccnz .Lsg_0
	s_waitcnt lgkmcnt(1)
	v_mul_f32_e32 v4, v40, v4
	v_mul_f32_e32 v5, v40, v5
	v_mul_f32_e32 v6, v40, v6
	v_mul_f32_e32 v7, v40, v7
	s_waitcnt lgkmcnt(0)
	v_mul_f32_e32 v0, v40, v0
	v_mul_f32_e32 v1, v40, v1
	v_mul_f32_e32 v2, v40, v2
	v_mul_f32_e32 v3, v40, v3
	v_cvt_pk_f16_f32 v3, v2, v3
	v_cvt_pk_f16_f32 v2, v0, v1
	v_cvt_pk_f16_f32 v1, v6, v7
	v_cvt_pk_f16_f32 v0, v4, v5
	s_branch .Lsgdone_0
.Lsg_0:
	s_waitcnt lgkmcnt(1)
	v_mul_f32_e32 v4, v40, v4
	v_mul_f32_e32 v17, 0xbfb8aa3b, v4
	v_exp_f32_e32 v17, v17
	v_mul_f32_e32 v5, v40, v5
	v_mul_f32_e32 v6, v40, v6
	v_mul_f32_e32 v7, v40, v7
	v_add_f32_e32 v17, 1.0, v17
	v_rcp_f32_e32 v17, v17
	s_waitcnt lgkmcnt(0)
	v_mul_f32_e32 v0, v40, v0
	v_mul_f32_e32 v1, v40, v1
	v_mul_f32_e32 v2, v40, v2
	v_mul_f32_e32 v18, v4, v17
	v_cndmask_b32_e64 v17, v17, v18, s[14:15]
	v_cndmask_b32_e64 v4, v17, v4, s[12:13]
	v_mul_f32_e32 v17, 0xbfb8aa3b, v5
	v_exp_f32_e32 v17, v17
	v_mul_f32_e32 v3, v40, v3
	v_add_f32_e32 v17, 1.0, v17
	v_rcp_f32_e32 v17, v17
	s_nop 0
	v_mul_f32_e32 v18, v5, v17
	v_cndmask_b32_e64 v17, v17, v18, s[14:15]
	v_cndmask_b32_e64 v5, v17, v5, s[12:13]
	v_mul_f32_e32 v17, 0xbfb8aa3b, v6
	v_exp_f32_e32 v17, v17
	s_nop 0
	v_add_f32_e32 v17, 1.0, v17
	v_rcp_f32_e32 v17, v17
	s_nop 0
	v_mul_f32_e32 v18, v6, v17
	v_cndmask_b32_e64 v17, v17, v18, s[14:15]
	v_cndmask_b32_e64 v6, v17, v6, s[12:13]
	v_mul_f32_e32 v17, 0xbfb8aa3b, v7
	v_exp_f32_e32 v17, v17
	s_nop 0
	v_add_f32_e32 v17, 1.0, v17
	v_rcp_f32_e32 v17, v17
	s_nop 0
	v_mul_f32_e32 v18, v7, v17
	v_cndmask_b32_e64 v17, v17, v18, s[14:15]
	v_cndmask_b32_e64 v7, v17, v7, s[12:13]
	v_mul_f32_e32 v17, 0xbfb8aa3b, v0
	v_exp_f32_e32 v17, v17
	s_nop 0
	v_add_f32_e32 v17, 1.0, v17
	v_rcp_f32_e32 v17, v17
	s_nop 0
	v_mul_f32_e32 v18, v0, v17
	v_cndmask_b32_e64 v17, v17, v18, s[14:15]
	v_cndmask_b32_e64 v0, v17, v0, s[12:13]
	v_mul_f32_e32 v17, 0xbfb8aa3b, v1
	v_exp_f32_e32 v17, v17
	s_nop 0
	v_add_f32_e32 v17, 1.0, v17
	v_rcp_f32_e32 v17, v17
	s_nop 0
	v_mul_f32_e32 v18, v1, v17
	v_cndmask_b32_e64 v17, v17, v18, s[14:15]
	v_cndmask_b32_e64 v1, v17, v1, s[12:13]
	v_mul_f32_e32 v17, 0xbfb8aa3b, v2
	v_exp_f32_e32 v17, v17
	s_nop 0
	v_add_f32_e32 v17, 1.0, v17
	v_rcp_f32_e32 v17, v17
	s_nop 0
	v_mul_f32_e32 v18, v2, v17
	v_cndmask_b32_e64 v17, v17, v18, s[14:15]
	v_cndmask_b32_e64 v2, v17, v2, s[12:13]
	v_mul_f32_e32 v17, 0xbfb8aa3b, v3
	v_exp_f32_e32 v17, v17
	s_nop 0
	v_add_f32_e32 v17, 1.0, v17
	v_rcp_f32_e32 v17, v17
	s_nop 0
	v_mul_f32_e32 v18, v3, v17
	v_cndmask_b32_e64 v17, v17, v18, s[14:15]
	v_cndmask_b32_e64 v3, v17, v3, s[12:13]
	v_cvt_pk_f16_f32 v3, v2, v3
	v_cvt_pk_f16_f32 v2, v0, v1
	v_cvt_pk_f16_f32 v1, v6, v7
	v_cvt_pk_f16_f32 v0, v4, v5
.Lsgdone_0:
	s_and_saveexec_b64 s[6:7], s[10:11]
	s_cbranch_execz .LBB0_358
	v_mad_i64_i32 v[4:5], s[34:35], v16, s68, v[8:9]
	global_store_dwordx4 v[4:5], v[0:3], off nt

.LBB0_366:
	s_or_b64 exec, exec, s[36:37]
	s_andn2_b64 vcc, exec, s[12:13]
	s_cbranch_vccnz .Lsg_1
	s_waitcnt lgkmcnt(1)
	v_mul_f32_e32 v4, v40, v4
	v_mul_f32_e32 v5, v40, v5
	v_mul_f32_e32 v6, v40, v6
	v_mul_f32_e32 v7, v40, v7
	s_waitcnt lgkmcnt(0)
	v_mul_f32_e32 v0, v40, v0
	v_mul_f32_e32 v1, v40, v1
	v_mul_f32_e32 v2, v40, v2
	v_mul_f32_e32 v3, v40, v3
	v_cvt_pk_f16_f32 v3, v2, v3
	v_cvt_pk_f16_f32 v2, v0, v1
	v_cvt_pk_f16_f32 v1, v6, v7
	v_cvt_pk_f16_f32 v0, v4, v5
	s_branch .Lsgdone_1
.Lsg_1:
	s_waitcnt lgkmcnt(1)
	v_mul_f32_e32 v4, v40, v4
	v_mul_f32_e32 v17, 0xbfb8aa3b, v4
	v_exp_f32_e32 v17, v17
	v_mul_f32_e32 v5, v40, v5
	v_mul_f32_e32 v6, v40, v6
	v_mul_f32_e32 v7, v40, v7
	v_add_f32_e32 v17, 1.0, v17
	v_rcp_f32_e32 v17, v17
	s_waitcnt lgkmcnt(0)
	v_mul_f32_e32 v0, v40, v0
	v_mul_f32_e32 v1, v40, v1
	v_mul_f32_e32 v2, v40, v2
	v_mul_f32_e32 v19, v4, v17
	v_cndmask_b32_e64 v17, v17, v19, s[14:15]
	v_cndmask_b32_e64 v4, v17, v4, s[12:13]
	v_mul_f32_e32 v17, 0xbfb8aa3b, v5
	v_exp_f32_e32 v17, v17
	v_mul_f32_e32 v3, v40, v3
	v_add_f32_e32 v17, 1.0, v17
	v_rcp_f32_e32 v17, v17
	s_nop 0
	v_mul_f32_e32 v19, v5, v17
	v_cndmask_b32_e64 v17, v17, v19, s[14:15]
	v_cndmask_b32_e64 v5, v17, v5, s[12:13]
	v_mul_f32_e32 v17, 0xbfb8aa3b, v6
	v_exp_f32_e32 v17, v17
	s_nop 0
	v_add_f32_e32 v17, 1.0, v17
	v_rcp_f32_e32 v17, v17
	s_nop 0
	v_mul_f32_e32 v19, v6, v17
	v_cndmask_b32_e64 v17, v17, v19, s[14:15]
	v_cndmask_b32_e64 v6, v17, v6, s[12:13]
	v_mul_f32_e32 v17, 0xbfb8aa3b, v7
	v_exp_f32_e32 v17, v17
	s_nop 0
	v_add_f32_e32 v17, 1.0, v17
	v_rcp_f32_e32 v17, v17
	s_nop 0
	v_mul_f32_e32 v19, v7, v17
	v_cndmask_b32_e64 v17, v17, v19, s[14:15]
	v_cndmask_b32_e64 v7, v17, v7, s[12:13]
	v_mul_f32_e32 v17, 0xbfb8aa3b, v0
	v_exp_f32_e32 v17, v17
	s_nop 0
	v_add_f32_e32 v17, 1.0, v17
	v_rcp_f32_e32 v17, v17
	s_nop 0
	v_mul_f32_e32 v19, v0, v17
	v_cndmask_b32_e64 v17, v17, v19, s[14:15]
	v_cndmask_b32_e64 v0, v17, v0, s[12:13]
	v_mul_f32_e32 v17, 0xbfb8aa3b, v1
	v_exp_f32_e32 v17, v17
	s_nop 0
	v_add_f32_e32 v17, 1.0, v17
	v_rcp_f32_e32 v17, v17
	s_nop 0
	v_mul_f32_e32 v19, v1, v17
	v_cndmask_b32_e64 v17, v17, v19, s[14:15]
	v_cndmask_b32_e64 v1, v17, v1, s[12:13]
	v_mul_f32_e32 v17, 0xbfb8aa3b, v2
	v_exp_f32_e32 v17, v17
	s_nop 0
	v_add_f32_e32 v17, 1.0, v17
	v_rcp_f32_e32 v17, v17
	s_nop 0
	v_mul_f32_e32 v19, v2, v17
	v_cndmask_b32_e64 v17, v17, v19, s[14:15]
	v_cndmask_b32_e64 v2, v17, v2, s[12:13]
	v_mul_f32_e32 v17, 0xbfb8aa3b, v3
	v_exp_f32_e32 v17, v17
	s_nop 0
	v_add_f32_e32 v17, 1.0, v17
	v_rcp_f32_e32 v17, v17
	s_nop 0
	v_mul_f32_e32 v19, v3, v17
	v_cndmask_b32_e64 v17, v17, v19, s[14:15]
	v_cndmask_b32_e64 v3, v17, v3, s[12:13]
	v_cvt_pk_f16_f32 v3, v2, v3
	v_cvt_pk_f16_f32 v2, v0, v1
	v_cvt_pk_f16_f32 v1, v6, v7
	v_cvt_pk_f16_f32 v0, v4, v5
.Lsgdone_1:
	s_and_saveexec_b64 s[34:35], s[10:11]
	s_cbranch_execnz .LBB0_369
	s_or_b64 exec, exec, s[34:35]
	s_and_b64 vcc, exec, s[6:7]
	s_cbranch_vccz .LBB0_370

.Lsg_2:
	s_waitcnt lgkmcnt(1)
	v_mul_f32_e32 v4, v40, v4
	v_mul_f32_e32 v19, 0xbfb8aa3b, v4
	v_exp_f32_e32 v19, v19
	v_mul_f32_e32 v5, v40, v5
	v_mul_f32_e32 v6, v40, v6
	v_mul_f32_e32 v7, v40, v7
	v_add_f32_e32 v19, 1.0, v19
	v_rcp_f32_e32 v19, v19
	s_waitcnt lgkmcnt(0)
	v_mul_f32_e32 v0, v40, v0
	v_mul_f32_e32 v1, v40, v1
	v_mul_f32_e32 v2, v40, v2
	v_mul_f32_e32 v21, v4, v19
	v_cndmask_b32_e64 v19, v19, v21, s[14:15]
	v_cndmask_b32_e64 v4, v19, v4, s[12:13]
	v_mul_f32_e32 v19, 0xbfb8aa3b, v5
	v_exp_f32_e32 v19, v19
	v_mul_f32_e32 v3, v40, v3
	v_add_f32_e32 v19, 1.0, v19
	v_rcp_f32_e32 v19, v19
	s_nop 0
	v_mul_f32_e32 v21, v5, v19
	v_cndmask_b32_e64 v19, v19, v21, s[14:15]
	v_cndmask_b32_e64 v5, v19, v5, s[12:13]
	v_mul_f32_e32 v19, 0xbfb8aa3b, v6
	v_exp_f32_e32 v19, v19
	s_nop 0
	v_add_f32_e32 v19, 1.0, v19
	v_rcp_f32_e32 v19, v19
	s_nop 0
	v_mul_f32_e32 v21, v6, v19
	v_cndmask_b32_e64 v19, v19, v21, s[14:15]
	v_cndmask_b32_e64 v6, v19, v6, s[12:13]
	v_mul_f32_e32 v19, 0xbfb8aa3b, v7
	v_exp_f32_e32 v19, v19
	s_nop 0
	v_add_f32_e32 v19, 1.0, v19
	v_rcp_f32_e32 v19, v19
	s_nop 0
	v_mul_f32_e32 v21, v7, v19
	v_cndmask_b32_e64 v19, v19, v21, s[14:15]
	v_cndmask_b32_e64 v7, v19, v7, s[12:13]
	v_mul_f32_e32 v19, 0xbfb8aa3b, v0
	v_exp_f32_e32 v19, v19
	s_nop 0
	v_add_f32_e32 v19, 1.0, v19
	v_rcp_f32_e32 v19, v19
	s_nop 0
	v_mul_f32_e32 v21, v0, v19
	v_cndmask_b32_e64 v19, v19, v21, s[14:15]
	v_cndmask_b32_e64 v0, v19, v0, s[12:13]
	v_mul_f32_e32 v19, 0xbfb8aa3b, v1
	v_exp_f32_e32 v19, v19
	s_nop 0
	v_add_f32_e32 v19, 1.0, v19
	v_rcp_f32_e32 v19, v19
	s_nop 0
	v_mul_f32_e32 v21, v1, v19
	v_cndmask_b32_e64 v19, v19, v21, s[14:15]
	v_cndmask_b32_e64 v1, v19, v1, s[12:13]
	v_mul_f32_e32 v19, 0xbfb8aa3b, v2
	v_exp_f32_e32 v19, v19
	s_nop 0
	v_add_f32_e32 v19, 1.0, v19
	v_rcp_f32_e32 v19, v19
	s_nop 0
	v_mul_f32_e32 v21, v2, v19
	v_cndmask_b32_e64 v19, v19, v21, s[14:15]
	v_cndmask_b32_e64 v2, v19, v2, s[12:13]
	v_mul_f32_e32 v19, 0xbfb8aa3b, v3
	v_exp_f32_e32 v19, v19
	s_nop 0
	v_add_f32_e32 v19, 1.0, v19
	v_rcp_f32_e32 v19, v19
	s_nop 0
	v_mul_f32_e32 v21, v3, v19
	v_cndmask_b32_e64 v19, v19, v21, s[14:15]
	v_cndmask_b32_e64 v3, v19, v3, s[12:13]
	v_cvt_pk_f16_f32 v3, v2, v3
	v_cvt_pk_f16_f32 v2, v0, v1
	v_cvt_pk_f16_f32 v1, v6, v7
	v_cvt_pk_f16_f32 v0, v4, v5
.Lsgdone_2:
	s_and_saveexec_b64 s[2:3], s[10:11]
	s_cbranch_execnz .LBB0_389
	s_or_b64 exec, exec, s[2:3]
	s_and_b64 vcc, exec, s[6:7]
	s_cbranch_vccz .LBB0_390

.LBB0_444:
	s_or_b64 exec, exec, s[26:27]
	s_andn2_b64 vcc, exec, s[12:13]
	s_cbranch_vccnz .Lsg_8
	v_mul_f32_e32 v8, v49, v52
	v_mul_f32_e32 v9, v49, v9
	v_mul_f32_e32 v10, v49, v50
	v_mov_b32_e32 v50, v10
	v_mul_f32_e32 v10, v49, v40
	v_cvt_pk_f16_f32 v8, v8, v50
	v_mov_b32_e32 v40, v10
	v_mul_f32_e32 v10, v49, v29
	v_mov_b32_e32 v29, v10
	v_mul_f32_e32 v10, v49, v28
	v_mul_f32_e32 v11, v49, v21
	v_mov_b32_e32 v21, v11
	v_mul_f32_e32 v11, v49, v19
	v_cvt_pk_f16_f32 v10, v10, v21
	v_cvt_pk_f16_f32 v11, v11, v9
	v_cvt_pk_f16_f32 v9, v40, v29
	s_branch .Lsgdone_8
.Lsg_8:
	v_mul_f32_e32 v8, v49, v52
	v_mul_f32_e32 v10, 0xbfb8aa3b, v8
	v_exp_f32_e32 v10, v10
	v_mul_f32_e32 v9, v49, v9
	v_add_f32_e32 v10, 1.0, v10
	v_rcp_f32_e32 v10, v10
	s_nop 0
	v_mul_f32_e32 v11, v8, v10
	v_cndmask_b32_e64 v10, v10, v11, s[14:15]
	v_cndmask_b32_e64 v8, v10, v8, s[12:13]
	v_mul_f32_e32 v10, v49, v50
	v_mul_f32_e32 v11, 0xbfb8aa3b, v10
	v_exp_f32_e32 v11, v11
	s_nop 0
	v_add_f32_e32 v11, 1.0, v11
	v_rcp_f32_e32 v11, v11
	s_nop 0
	v_mul_f32_e32 v50, v10, v11
	v_cndmask_b32_e64 v11, v11, v50, s[14:15]
	v_cndmask_b32_e64 v50, v11, v10, s[12:13]
	v_mul_f32_e32 v10, v49, v40
	v_mul_f32_e32 v11, 0xbfb8aa3b, v10
	v_exp_f32_e32 v11, v11
	v_cvt_pk_f16_f32 v8, v8, v50
	v_add_f32_e32 v11, 1.0, v11
	v_rcp_f32_e32 v11, v11
	s_nop 0
	v_mul_f32_e32 v40, v10, v11
	v_cndmask_b32_e64 v11, v11, v40, s[14:15]
	v_cndmask_b32_e64 v40, v11, v10, s[12:13]
	v_mul_f32_e32 v10, v49, v29
	v_mul_f32_e32 v11, 0xbfb8aa3b, v10
	v_exp_f32_e32 v11, v11
	s_nop 0
	v_add_f32_e32 v11, 1.0, v11
	v_rcp_f32_e32 v11, v11
	s_nop 0
	v_mul_f32_e32 v29, v10, v11
	v_cndmask_b32_e64 v11, v11, v29, s[14:15]
	v_cndmask_b32_e64 v29, v11, v10, s[12:13]
	v_mul_f32_e32 v10, v49, v28
	v_mul_f32_e32 v11, 0xbfb8aa3b, v10
	v_exp_f32_e32 v11, v11
	s_nop 0
	v_add_f32_e32 v11, 1.0, v11
	v_rcp_f32_e32 v11, v11
	s_nop 0
	v_mul_f32_e32 v28, v10, v11
	v_cndmask_b32_e64 v11, v11, v28, s[14:15]
	v_cndmask_b32_e64 v10, v11, v10, s[12:13]
	v_mul_f32_e32 v11, v49, v21
	v_mul_f32_e32 v21, 0xbfb8aa3b, v11
	v_exp_f32_e32 v21, v21
	s_nop 0
	v_add_f32_e32 v21, 1.0, v21
	v_rcp_f32_e32 v21, v21
	s_nop 0
	v_mul_f32_e32 v28, v11, v21
	v_cndmask_b32_e64 v21, v21, v28, s[14:15]
	v_cndmask_b32_e64 v21, v21, v11, s[12:13]
	v_mul_f32_e32 v11, v49, v19
	v_mul_f32_e32 v19, 0xbfb8aa3b, v11
	v_exp_f32_e32 v19, v19
	v_cvt_pk_f16_f32 v10, v10, v21
	v_add_f32_e32 v19, 1.0, v19
	v_rcp_f32_e32 v19, v19
	s_nop 0
	v_mul_f32_e32 v28, v11, v19
	v_cndmask_b32_e64 v19, v19, v28, s[14:15]
	v_cndmask_b32_e64 v11, v19, v11, s[12:13]
	v_mul_f32_e32 v19, 0xbfb8aa3b, v9
	v_exp_f32_e32 v19, v19
	s_nop 0
	v_add_f32_e32 v19, 1.0, v19
	v_rcp_f32_e32 v19, v19
	s_nop 0
	v_mul_f32_e32 v28, v9, v19
	v_cndmask_b32_e64 v19, v19, v28, s[14:15]
	v_cndmask_b32_e64 v9, v19, v9, s[12:13]
	v_cvt_pk_f16_f32 v11, v11, v9
	v_cvt_pk_f16_f32 v9, v40, v29

.LBB0_453:
	s_or_b64 exec, exec, s[26:27]
	s_andn2_b64 vcc, exec, s[12:13]
	s_cbranch_vccnz .Lsg_9
	v_mul_f32_e32 v8, v49, v52
	v_mul_f32_e32 v9, v49, v9
	v_mul_f32_e32 v10, v49, v50
	v_mov_b32_e32 v50, v10
	v_mul_f32_e32 v10, v49, v40
	v_cvt_pk_f16_f32 v8, v8, v50
	v_mov_b32_e32 v40, v10
	v_mul_f32_e32 v10, v49, v21
	v_mov_b32_e32 v21, v10
	v_mul_f32_e32 v10, v49, v19
	v_mul_f32_e32 v11, v49, v17
	v_mov_b32_e32 v17, v11
	v_mul_f32_e32 v11, v49, v15
	v_cvt_pk_f16_f32 v10, v10, v17
	v_cvt_pk_f16_f32 v11, v11, v9
	v_cvt_pk_f16_f32 v9, v40, v21
	s_branch .Lsgdone_9
.Lsg_9:
	v_mul_f32_e32 v8, v49, v52
	v_mul_f32_e32 v10, 0xbfb8aa3b, v8
	v_exp_f32_e32 v10, v10
	v_mul_f32_e32 v9, v49, v9
	v_add_f32_e32 v10, 1.0, v10
	v_rcp_f32_e32 v10, v10
	s_nop 0
	v_mul_f32_e32 v11, v8, v10
	v_cndmask_b32_e64 v10, v10, v11, s[14:15]
	v_cndmask_b32_e64 v8, v10, v8, s[12:13]
	v_mul_f32_e32 v10, v49, v50
	v_mul_f32_e32 v11, 0xbfb8aa3b, v10
	v_exp_f32_e32 v11, v11
	s_nop 0
	v_add_f32_e32 v11, 1.0, v11
	v_rcp_f32_e32 v11, v11
	s_nop 0
	v_mul_f32_e32 v50, v10, v11
	v_cndmask_b32_e64 v11, v11, v50, s[14:15]
	v_cndmask_b32_e64 v50, v11, v10, s[12:13]
	v_mul_f32_e32 v10, v49, v40
	v_mul_f32_e32 v11, 0xbfb8aa3b, v10
	v_exp_f32_e32 v11, v11
	v_cvt_pk_f16_f32 v8, v8, v50
	v_add_f32_e32 v11, 1.0, v11
	v_rcp_f32_e32 v11, v11
	s_nop 0
	v_mul_f32_e32 v40, v10, v11
	v_cndmask_b32_e64 v11, v11, v40, s[14:15]
	v_cndmask_b32_e64 v40, v11, v10, s[12:13]
	v_mul_f32_e32 v10, v49, v21
	v_mul_f32_e32 v11, 0xbfb8aa3b, v10
	v_exp_f32_e32 v11, v11
	s_nop 0
	v_add_f32_e32 v11, 1.0, v11
	v_rcp_f32_e32 v11, v11
	s_nop 0
	v_mul_f32_e32 v21, v10, v11
	v_cndmask_b32_e64 v11, v11, v21, s[14:15]
	v_cndmask_b32_e64 v21, v11, v10, s[12:13]
	v_mul_f32_e32 v10, v49, v19
	v_mul_f32_e32 v11, 0xbfb8aa3b, v10
	v_exp_f32_e32 v11, v11
	s_nop 0
	v_add_f32_e32 v11, 1.0, v11
	v_rcp_f32_e32 v11, v11
	s_nop 0
	v_mul_f32_e32 v19, v10, v11
	v_cndmask_b32_e64 v11, v11, v19, s[14:15]
	v_cndmask_b32_e64 v10, v11, v10, s[12:13]
	v_mul_f32_e32 v11, v49, v17
	v_mul_f32_e32 v17, 0xbfb8aa3b, v11
	v_exp_f32_e32 v17, v17
	s_nop 0
	v_add_f32_e32 v17, 1.0, v17
	v_rcp_f32_e32 v17, v17
	s_nop 0
	v_mul_f32_e32 v19, v11, v17
	v_cndmask_b32_e64 v17, v17, v19, s[14:15]
	v_cndmask_b32_e64 v17, v17, v11, s[12:13]
	v_mul_f32_e32 v11, v49, v15
	v_mul_f32_e32 v15, 0xbfb8aa3b, v11
	v_exp_f32_e32 v15, v15
	v_cvt_pk_f16_f32 v10, v10, v17
	v_add_f32_e32 v15, 1.0, v15
	v_rcp_f32_e32 v15, v15
	s_nop 0
	v_mul_f32_e32 v19, v11, v15
	v_cndmask_b32_e64 v15, v15, v19, s[14:15]
	v_cndmask_b32_e64 v11, v15, v11, s[12:13]
	v_mul_f32_e32 v15, 0xbfb8aa3b, v9
	v_exp_f32_e32 v15, v15
	s_nop 0
	v_add_f32_e32 v15, 1.0, v15
	v_rcp_f32_e32 v15, v15
	s_nop 0
	v_mul_f32_e32 v19, v9, v15
	v_cndmask_b32_e64 v15, v15, v19, s[14:15]
	v_cndmask_b32_e64 v9, v15, v9, s[12:13]
	v_cvt_pk_f16_f32 v11, v11, v9
	v_cvt_pk_f16_f32 v9, v40, v21

.LBB0_479:
	s_or_b64 exec, exec, s[26:27]
	s_andn2_b64 vcc, exec, s[12:13]
	s_cbranch_vccnz .Lsg_11
	v_mul_f32_e32 v8, v49, v50
	v_mul_f32_e32 v9, v49, v9
	v_mul_f32_e32 v10, v49, v29
	v_mov_b32_e32 v29, v10
	v_mul_f32_e32 v10, v49, v28
	v_cvt_pk_f16_f32 v8, v8, v29
	v_mov_b32_e32 v28, v10
	v_mul_f32_e32 v10, v49, v21
	v_mov_b32_e32 v21, v10
	v_mul_f32_e32 v10, v49, v19
	v_mul_f32_e32 v11, v49, v15
	v_mov_b32_e32 v15, v11
	v_mul_f32_e32 v11, v49, v14
	v_cvt_pk_f16_f32 v10, v10, v15
	v_cvt_pk_f16_f32 v11, v11, v9
	v_cvt_pk_f16_f32 v9, v28, v21
	s_branch .Lsgdone_11
.Lsg_11:
	v_mul_f32_e32 v8, v49, v50
	v_mul_f32_e32 v10, 0xbfb8aa3b, v8
	v_exp_f32_e32 v10, v10
	v_mul_f32_e32 v9, v49, v9
	v_add_f32_e32 v10, 1.0, v10
	v_rcp_f32_e32 v10, v10
	s_nop 0
	v_mul_f32_e32 v11, v8, v10
	v_cndmask_b32_e64 v10, v10, v11, s[14:15]
	v_cndmask_b32_e64 v8, v10, v8, s[12:13]
	v_mul_f32_e32 v10, v49, v29
	v_mul_f32_e32 v11, 0xbfb8aa3b, v10
	v_exp_f32_e32 v11, v11
	s_nop 0
	v_add_f32_e32 v11, 1.0, v11
	v_rcp_f32_e32 v11, v11
	s_nop 0
	v_mul_f32_e32 v29, v10, v11
	v_cndmask_b32_e64 v11, v11, v29, s[14:15]
	v_cndmask_b32_e64 v29, v11, v10, s[12:13]
	v_mul_f32_e32 v10, v49, v28
	v_mul_f32_e32 v11, 0xbfb8aa3b, v10
	v_exp_f32_e32 v11, v11
	v_cvt_pk_f16_f32 v8, v8, v29
	v_add_f32_e32 v11, 1.0, v11
	v_rcp_f32_e32 v11, v11
	s_nop 0
	v_mul_f32_e32 v28, v10, v11
	v_cndmask_b32_e64 v11, v11, v28, s[14:15]
	v_cndmask_b32_e64 v28, v11, v10, s[12:13]
	v_mul_f32_e32 v10, v49, v21
	v_mul_f32_e32 v11, 0xbfb8aa3b, v10
	v_exp_f32_e32 v11, v11
	s_nop 0
	v_add_f32_e32 v11, 1.0, v11
	v_rcp_f32_e32 v11, v11
	s_nop 0
	v_mul_f32_e32 v21, v10, v11
	v_cndmask_b32_e64 v11, v11, v21, s[14:15]
	v_cndmask_b32_e64 v21, v11, v10, s[12:13]
	v_mul_f32_e32 v10, v49, v19
	v_mul_f32_e32 v11, 0xbfb8aa3b, v10
	v_exp_f32_e32 v11, v11
	s_nop 0
	v_add_f32_e32 v11, 1.0, v11
	v_rcp_f32_e32 v11, v11
	s_nop 0
	v_mul_f32_e32 v19, v10, v11
	v_cndmask_b32_e64 v11, v11, v19, s[14:15]
	v_cndmask_b32_e64 v10, v11, v10, s[12:13]
	v_mul_f32_e32 v11, v49, v15
	v_mul_f32_e32 v15, 0xbfb8aa3b, v11
	v_exp_f32_e32 v15, v15
	s_nop 0
	v_add_f32_e32 v15, 1.0, v15
	v_rcp_f32_e32 v15, v15
	s_nop 0
	v_mul_f32_e32 v19, v11, v15
	v_cndmask_b32_e64 v15, v15, v19, s[14:15]
	v_cndmask_b32_e64 v15, v15, v11, s[12:13]
	v_mul_f32_e32 v11, v49, v14
	v_mul_f32_e32 v14, 0xbfb8aa3b, v11
	v_exp_f32_e32 v14, v14
	v_cvt_pk_f16_f32 v10, v10, v15
	v_add_f32_e32 v14, 1.0, v14
	v_rcp_f32_e32 v14, v14
	s_nop 0
	v_mul_f32_e32 v19, v11, v14
	v_cndmask_b32_e64 v14, v14, v19, s[14:15]
	v_cndmask_b32_e64 v11, v14, v11, s[12:13]
	v_mul_f32_e32 v14, 0xbfb8aa3b, v9
	v_exp_f32_e32 v14, v14
	s_nop 0
	v_add_f32_e32 v14, 1.0, v14
	v_rcp_f32_e32 v14, v14
	s_nop 0
	v_mul_f32_e32 v19, v9, v14
	v_cndmask_b32_e64 v14, v14, v19, s[14:15]
	v_cndmask_b32_e64 v9, v14, v9, s[12:13]
	v_cvt_pk_f16_f32 v11, v11, v9
	v_cvt_pk_f16_f32 v9, v28, v21

.LBB0_496:
	s_or_b64 exec, exec, s[26:27]
	s_andn2_b64 vcc, exec, s[12:13]
	s_cbranch_vccnz .Lsg_12
	v_mul_f32_e32 v8, v49, v51
	v_mul_f32_e32 v9, v49, v9
	v_mul_f32_e32 v10, v49, v40
	v_mov_b32_e32 v40, v10
	v_mul_f32_e32 v10, v49, v29
	v_cvt_pk_f16_f32 v8, v8, v40
	v_mov_b32_e32 v29, v10
	v_mul_f32_e32 v10, v49, v28
	v_mov_b32_e32 v28, v10
	v_mul_f32_e32 v10, v49, v21
	v_mul_f32_e32 v11, v49, v19
	v_mov_b32_e32 v19, v11
	v_mul_f32_e32 v11, v49, v17
	v_cvt_pk_f16_f32 v10, v10, v19
	v_cvt_pk_f16_f32 v11, v11, v9
	v_cvt_pk_f16_f32 v9, v29, v28
	s_branch .Lsgdone_12
.Lsg_12:
	v_mul_f32_e32 v8, v49, v51
	v_mul_f32_e32 v10, 0xbfb8aa3b, v8
	v_exp_f32_e32 v10, v10
	v_mul_f32_e32 v9, v49, v9
	v_add_f32_e32 v10, 1.0, v10
	v_rcp_f32_e32 v10, v10
	s_nop 0
	v_mul_f32_e32 v11, v8, v10
	v_cndmask_b32_e64 v10, v10, v11, s[14:15]
	v_cndmask_b32_e64 v8, v10, v8, s[12:13]
	v_mul_f32_e32 v10, v49, v40
	v_mul_f32_e32 v11, 0xbfb8aa3b, v10
	v_exp_f32_e32 v11, v11
	s_nop 0
	v_add_f32_e32 v11, 1.0, v11
	v_rcp_f32_e32 v11, v11
	s_nop 0
	v_mul_f32_e32 v40, v10, v11
	v_cndmask_b32_e64 v11, v11, v40, s[14:15]
	v_cndmask_b32_e64 v40, v11, v10, s[12:13]
	v_mul_f32_e32 v10, v49, v29
	v_mul_f32_e32 v11, 0xbfb8aa3b, v10
	v_exp_f32_e32 v11, v11
	v_cvt_pk_f16_f32 v8, v8, v40
	v_add_f32_e32 v11, 1.0, v11
	v_rcp_f32_e32 v11, v11
	s_nop 0
	v_mul_f32_e32 v29, v10, v11
	v_cndmask_b32_e64 v11, v11, v29, s[14:15]
	v_cndmask_b32_e64 v29, v11, v10, s[12:13]
	v_mul_f32_e32 v10, v49, v28
	v_mul_f32_e32 v11, 0xbfb8aa3b, v10
	v_exp_f32_e32 v11, v11
	s_nop 0
	v_add_f32_e32 v11, 1.0, v11
	v_rcp_f32_e32 v11, v11
	s_nop 0
	v_mul_f32_e32 v28, v10, v11
	v_cndmask_b32_e64 v11, v11, v28, s[14:15]
	v_cndmask_b32_e64 v28, v11, v10, s[12:13]
	v_mul_f32_e32 v10, v49, v21
	v_mul_f32_e32 v11, 0xbfb8aa3b, v10
	v_exp_f32_e32 v11, v11
	s_nop 0
	v_add_f32_e32 v11, 1.0, v11
	v_rcp_f32_e32 v11, v11
	s_nop 0
	v_mul_f32_e32 v21, v10, v11
	v_cndmask_b32_e64 v11, v11, v21, s[14:15]
	v_cndmask_b32_e64 v10, v11, v10, s[12:13]
	v_mul_f32_e32 v11, v49, v19
	v_mul_f32_e32 v19, 0xbfb8aa3b, v11
	v_exp_f32_e32 v19, v19
	s_nop 0
	v_add_f32_e32 v19, 1.0, v19
	v_rcp_f32_e32 v19, v19
	s_nop 0
	v_mul_f32_e32 v21, v11, v19
	v_cndmask_b32_e64 v19, v19, v21, s[14:15]
	v_cndmask_b32_e64 v19, v19, v11, s[12:13]
	v_mul_f32_e32 v11, v49, v17
	v_mul_f32_e32 v17, 0xbfb8aa3b, v11
	v_exp_f32_e32 v17, v17
	v_cvt_pk_f16_f32 v10, v10, v19
	v_add_f32_e32 v17, 1.0, v17
	v_rcp_f32_e32 v17, v17
	s_nop 0
	v_mul_f32_e32 v21, v11, v17
	v_cndmask_b32_e64 v17, v17, v21, s[14:15]
	v_cndmask_b32_e64 v11, v17, v11, s[12:13]
	v_mul_f32_e32 v17, 0xbfb8aa3b, v9
	v_exp_f32_e32 v17, v17
	s_nop 0
	v_add_f32_e32 v17, 1.0, v17
	v_rcp_f32_e32 v17, v17
	s_nop 0
	v_mul_f32_e32 v21, v9, v17
	v_cndmask_b32_e64 v17, v17, v21, s[14:15]
	v_cndmask_b32_e64 v9, v17, v9, s[12:13]
	v_cvt_pk_f16_f32 v11, v11, v9
	v_cvt_pk_f16_f32 v9, v29, v28

.LBB0_505:
	s_or_b64 exec, exec, s[26:27]
	s_andn2_b64 vcc, exec, s[12:13]
	s_cbranch_vccnz .Lsg_13
	v_mul_f32_e32 v8, v49, v40
	v_mul_f32_e32 v9, v49, v9
	v_mul_f32_e32 v10, v49, v28
	v_mov_b32_e32 v28, v10
	v_mul_f32_e32 v10, v49, v21
	v_cvt_pk_f16_f32 v8, v8, v28
	v_mov_b32_e32 v21, v10
	v_mul_f32_e32 v10, v49, v17
	v_mov_b32_e32 v17, v10
	v_mul_f32_e32 v10, v49, v16
	v_mul_f32_e32 v11, v49, v15
	v_mov_b32_e32 v15, v11
	v_mul_f32_e32 v11, v49, v14
	v_cvt_pk_f16_f32 v10, v10, v15
	v_cvt_pk_f16_f32 v11, v11, v9
	v_cvt_pk_f16_f32 v9, v21, v17
	s_branch .Lsgdone_13
.Lsg_13:
	v_mul_f32_e32 v8, v49, v40
	v_mul_f32_e32 v10, 0xbfb8aa3b, v8
	v_exp_f32_e32 v10, v10
	v_mul_f32_e32 v9, v49, v9
	v_add_f32_e32 v10, 1.0, v10
	v_rcp_f32_e32 v10, v10
	s_nop 0
	v_mul_f32_e32 v11, v8, v10
	v_cndmask_b32_e64 v10, v10, v11, s[14:15]
	v_cndmask_b32_e64 v8, v10, v8, s[12:13]
	v_mul_f32_e32 v10, v49, v28
	v_mul_f32_e32 v11, 0xbfb8aa3b, v10
	v_exp_f32_e32 v11, v11
	s_nop 0
	v_add_f32_e32 v11, 1.0, v11
	v_rcp_f32_e32 v11, v11
	s_nop 0
	v_mul_f32_e32 v28, v10, v11
	v_cndmask_b32_e64 v11, v11, v28, s[14:15]
	v_cndmask_b32_e64 v28, v11, v10, s[12:13]
	v_mul_f32_e32 v10, v49, v21
	v_mul_f32_e32 v11, 0xbfb8aa3b, v10
	v_exp_f32_e32 v11, v11
	v_cvt_pk_f16_f32 v8, v8, v28
	v_add_f32_e32 v11, 1.0, v11
	v_rcp_f32_e32 v11, v11
	s_nop 0
	v_mul_f32_e32 v21, v10, v11
	v_cndmask_b32_e64 v11, v11, v21, s[14:15]
	v_cndmask_b32_e64 v21, v11, v10, s[12:13]
	v_mul_f32_e32 v10, v49, v17
	v_mul_f32_e32 v11, 0xbfb8aa3b, v10
	v_exp_f32_e32 v11, v11
	s_nop 0
	v_add_f32_e32 v11, 1.0, v11
	v_rcp_f32_e32 v11, v11
	s_nop 0
	v_mul_f32_e32 v17, v10, v11
	v_cndmask_b32_e64 v11, v11, v17, s[14:15]
	v_cndmask_b32_e64 v17, v11, v10, s[12:13]
	v_mul_f32_e32 v10, v49, v16
	v_mul_f32_e32 v11, 0xbfb8aa3b, v10
	v_exp_f32_e32 v11, v11
	s_nop 0
	v_add_f32_e32 v11, 1.0, v11
	v_rcp_f32_e32 v11, v11
	s_nop 0
	v_mul_f32_e32 v16, v10, v11
	v_cndmask_b32_e64 v11, v11, v16, s[14:15]
	v_cndmask_b32_e64 v10, v11, v10, s[12:13]
	v_mul_f32_e32 v11, v49, v15
	v_mul_f32_e32 v15, 0xbfb8aa3b, v11
	v_exp_f32_e32 v15, v15
	s_nop 0
	v_add_f32_e32 v15, 1.0, v15
	v_rcp_f32_e32 v15, v15
	s_nop 0
	v_mul_f32_e32 v16, v11, v15
	v_cndmask_b32_e64 v15, v15, v16, s[14:15]
	v_cndmask_b32_e64 v15, v15, v11, s[12:13]
	v_mul_f32_e32 v11, v49, v14
	v_mul_f32_e32 v14, 0xbfb8aa3b, v11
	v_exp_f32_e32 v14, v14
	v_cvt_pk_f16_f32 v10, v10, v15
	v_add_f32_e32 v14, 1.0, v14
	v_rcp_f32_e32 v14, v14
	s_nop 0
	v_mul_f32_e32 v16, v11, v14
	v_cndmask_b32_e64 v14, v14, v16, s[14:15]
	v_cndmask_b32_e64 v11, v14, v11, s[12:13]
	v_mul_f32_e32 v14, 0xbfb8aa3b, v9
	v_exp_f32_e32 v14, v14
	s_nop 0
	v_add_f32_e32 v14, 1.0, v14
	v_rcp_f32_e32 v14, v14
	s_nop 0
	v_mul_f32_e32 v16, v9, v14
	v_cndmask_b32_e64 v14, v14, v16, s[14:15]
	v_cndmask_b32_e64 v9, v14, v9, s[12:13]
	v_cvt_pk_f16_f32 v11, v11, v9
	v_cvt_pk_f16_f32 v9, v21, v17

.LBB0_522:
	s_or_b64 exec, exec, s[26:27]
	s_andn2_b64 vcc, exec, s[12:13]
	s_cbranch_vccnz .Lsg_14
	v_mul_f32_e32 v8, v49, v50
	v_mul_f32_e32 v9, v49, v9
	v_mul_f32_e32 v10, v49, v29
	v_mov_b32_e32 v29, v10
	v_mul_f32_e32 v10, v49, v28
	v_cvt_pk_f16_f32 v8, v8, v29
	v_mov_b32_e32 v28, v10
	v_mul_f32_e32 v10, v49, v21
	v_mov_b32_e32 v21, v10
	v_mul_f32_e32 v10, v49, v19
	v_mul_f32_e32 v11, v49, v18
	v_mov_b32_e32 v18, v11
	v_mul_f32_e32 v11, v49, v17
	v_cvt_pk_f16_f32 v10, v10, v18
	v_cvt_pk_f16_f32 v11, v11, v9
	v_cvt_pk_f16_f32 v9, v28, v21
	s_branch .Lsgdone_14
.Lsg_14:
	v_mul_f32_e32 v8, v49, v50
	v_mul_f32_e32 v10, 0xbfb8aa3b, v8
	v_exp_f32_e32 v10, v10
	v_mul_f32_e32 v9, v49, v9
	v_add_f32_e32 v10, 1.0, v10
	v_rcp_f32_e32 v10, v10
	s_nop 0
	v_mul_f32_e32 v11, v8, v10
	v_cndmask_b32_e64 v10, v10, v11, s[14:15]
	v_cndmask_b32_e64 v8, v10, v8, s[12:13]
	v_mul_f32_e32 v10, v49, v29
	v_mul_f32_e32 v11, 0xbfb8aa3b, v10
	v_exp_f32_e32 v11, v11
	s_nop 0
	v_add_f32_e32 v11, 1.0, v11
	v_rcp_f32_e32 v11, v11
	s_nop 0
	v_mul_f32_e32 v29, v10, v11
	v_cndmask_b32_e64 v11, v11, v29, s[14:15]
	v_cndmask_b32_e64 v29, v11, v10, s[12:13]
	v_mul_f32_e32 v10, v49, v28
	v_mul_f32_e32 v11, 0xbfb8aa3b, v10
	v_exp_f32_e32 v11, v11
	v_cvt_pk_f16_f32 v8, v8, v29
	v_add_f32_e32 v11, 1.0, v11
	v_rcp_f32_e32 v11, v11
	s_nop 0
	v_mul_f32_e32 v28, v10, v11
	v_cndmask_b32_e64 v11, v11, v28, s[14:15]
	v_cndmask_b32_e64 v28, v11, v10, s[12:13]
	v_mul_f32_e32 v10, v49, v21
	v_mul_f32_e32 v11, 0xbfb8aa3b, v10
	v_exp_f32_e32 v11, v11
	s_nop 0
	v_add_f32_e32 v11, 1.0, v11
	v_rcp_f32_e32 v11, v11
	s_nop 0
	v_mul_f32_e32 v21, v10, v11
	v_cndmask_b32_e64 v11, v11, v21, s[14:15]
	v_cndmask_b32_e64 v21, v11, v10, s[12:13]
	v_mul_f32_e32 v10, v49, v19
	v_mul_f32_e32 v11, 0xbfb8aa3b, v10
	v_exp_f32_e32 v11, v11
	s_nop 0
	v_add_f32_e32 v11, 1.0, v11
	v_rcp_f32_e32 v11, v11
	s_nop 0
	v_mul_f32_e32 v19, v10, v11
	v_cndmask_b32_e64 v11, v11, v19, s[14:15]
	v_cndmask_b32_e64 v10, v11, v10, s[12:13]
	v_mul_f32_e32 v11, v49, v18
	v_mul_f32_e32 v18, 0xbfb8aa3b, v11
	v_exp_f32_e32 v18, v18
	s_nop 0
	v_add_f32_e32 v18, 1.0, v18
	v_rcp_f32_e32 v18, v18
	s_nop 0
	v_mul_f32_e32 v19, v11, v18
	v_cndmask_b32_e64 v18, v18, v19, s[14:15]
	v_cndmask_b32_e64 v18, v18, v11, s[12:13]
	v_mul_f32_e32 v11, v49, v17
	v_mul_f32_e32 v17, 0xbfb8aa3b, v11
	v_exp_f32_e32 v17, v17
	v_cvt_pk_f16_f32 v10, v10, v18
	v_add_f32_e32 v17, 1.0, v17
	v_rcp_f32_e32 v17, v17
	s_nop 0
	v_mul_f32_e32 v19, v11, v17
	v_cndmask_b32_e64 v17, v17, v19, s[14:15]
	v_cndmask_b32_e64 v11, v17, v11, s[12:13]
	v_mul_f32_e32 v17, 0xbfb8aa3b, v9
	v_exp_f32_e32 v17, v17
	s_nop 0
	v_add_f32_e32 v17, 1.0, v17
	v_rcp_f32_e32 v17, v17
	s_nop 0
	v_mul_f32_e32 v19, v9, v17
	v_cndmask_b32_e64 v17, v17, v19, s[14:15]
	v_cndmask_b32_e64 v9, v17, v9, s[12:13]
	v_cvt_pk_f16_f32 v11, v11, v9
	v_cvt_pk_f16_f32 v9, v28, v21

.LBB0_531:
	s_or_b64 exec, exec, s[26:27]
	s_andn2_b64 vcc, exec, s[12:13]
	s_cbranch_vccnz .Lsg_15
	v_mul_f32_e32 v8, v49, v29
	v_mul_f32_e32 v9, v49, v9
	v_mul_f32_e32 v10, v49, v19
	v_mov_b32_e32 v19, v10
	v_mul_f32_e32 v10, v49, v18
	v_cvt_pk_f16_f32 v8, v8, v19
	v_mov_b32_e32 v18, v10
	v_mul_f32_e32 v10, v49, v17
	v_mov_b32_e32 v17, v10
	v_mul_f32_e32 v10, v49, v16
	v_mul_f32_e32 v11, v49, v15
	v_mov_b32_e32 v15, v11
	v_mul_f32_e32 v11, v49, v14
	v_cvt_pk_f16_f32 v10, v10, v15
	v_cvt_pk_f16_f32 v11, v11, v9
	v_cvt_pk_f16_f32 v9, v18, v17
	s_branch .Lsgdone_15
.Lsg_15:
	v_mul_f32_e32 v8, v49, v29
	v_mul_f32_e32 v10, 0xbfb8aa3b, v8
	v_exp_f32_e32 v10, v10
	v_mul_f32_e32 v9, v49, v9
	v_add_f32_e32 v10, 1.0, v10
	v_rcp_f32_e32 v10, v10
	s_nop 0
	v_mul_f32_e32 v11, v8, v10
	v_cndmask_b32_e64 v10, v10, v11, s[14:15]
	v_cndmask_b32_e64 v8, v10, v8, s[12:13]
	v_mul_f32_e32 v10, v49, v19
	v_mul_f32_e32 v11, 0xbfb8aa3b, v10
	v_exp_f32_e32 v11, v11
	s_nop 0
	v_add_f32_e32 v11, 1.0, v11
	v_rcp_f32_e32 v11, v11
	s_nop 0
	v_mul_f32_e32 v19, v10, v11
	v_cndmask_b32_e64 v11, v11, v19, s[14:15]
	v_cndmask_b32_e64 v19, v11, v10, s[12:13]
	v_mul_f32_e32 v10, v49, v18
	v_mul_f32_e32 v11, 0xbfb8aa3b, v10
	v_exp_f32_e32 v11, v11
	v_cvt_pk_f16_f32 v8, v8, v19
	v_add_f32_e32 v11, 1.0, v11
	v_rcp_f32_e32 v11, v11
	s_nop 0
	v_mul_f32_e32 v18, v10, v11
	v_cndmask_b32_e64 v11, v11, v18, s[14:15]
	v_cndmask_b32_e64 v18, v11, v10, s[12:13]
	v_mul_f32_e32 v10, v49, v17
	v_mul_f32_e32 v11, 0xbfb8aa3b, v10
	v_exp_f32_e32 v11, v11
	s_nop 0
	v_add_f32_e32 v11, 1.0, v11
	v_rcp_f32_e32 v11, v11
	s_nop 0
	v_mul_f32_e32 v17, v10, v11
	v_cndmask_b32_e64 v11, v11, v17, s[14:15]
	v_cndmask_b32_e64 v17, v11, v10, s[12:13]
	v_mul_f32_e32 v10, v49, v16
	v_mul_f32_e32 v11, 0xbfb8aa3b, v10
	v_exp_f32_e32 v11, v11
	s_nop 0
	v_add_f32_e32 v11, 1.0, v11
	v_rcp_f32_e32 v11, v11
	s_nop 0
	v_mul_f32_e32 v16, v10, v11
	v_cndmask_b32_e64 v11, v11, v16, s[14:15]
	v_cndmask_b32_e64 v10, v11, v10, s[12:13]
	v_mul_f32_e32 v11, v49, v15
	v_mul_f32_e32 v15, 0xbfb8aa3b, v11
	v_exp_f32_e32 v15, v15
	s_nop 0
	v_add_f32_e32 v15, 1.0, v15
	v_rcp_f32_e32 v15, v15
	s_nop 0
	v_mul_f32_e32 v16, v11, v15
	v_cndmask_b32_e64 v15, v15, v16, s[14:15]
	v_cndmask_b32_e64 v15, v15, v11, s[12:13]
	v_mul_f32_e32 v11, v49, v14
	v_mul_f32_e32 v14, 0xbfb8aa3b, v11
	v_exp_f32_e32 v14, v14
	v_cvt_pk_f16_f32 v10, v10, v15
	v_add_f32_e32 v14, 1.0, v14
	v_rcp_f32_e32 v14, v14
	s_nop 0
	v_mul_f32_e32 v16, v11, v14
	v_cndmask_b32_e64 v14, v14, v16, s[14:15]
	v_cndmask_b32_e64 v11, v14, v11, s[12:13]
	v_mul_f32_e32 v14, 0xbfb8aa3b, v9
	v_exp_f32_e32 v14, v14
	s_nop 0
	v_add_f32_e32 v14, 1.0, v14
	v_rcp_f32_e32 v14, v14
	s_nop 0
	v_mul_f32_e32 v16, v9, v14
	v_cndmask_b32_e64 v14, v14, v16, s[14:15]
	v_cndmask_b32_e64 v9, v14, v9, s[12:13]
	v_cvt_pk_f16_f32 v11, v11, v9
	v_cvt_pk_f16_f32 v9, v18, v17
